# v44 plus: P5,P8 epilogues read all eight per-row-group rstd values from LDS up front (later reads become v_mov), so those waits no longer drain the pending lane permutes
# speedup vs baseline: 1.0159x; 1.0018x over previous
;     __device__ __forceinline__ void operator()(const f32x4 (&acc)[2][2][4][2], const Unit& u, int wr, int wc, int fr, int fq) const {
;     ...
;         int slot = -1;
;         if (tab) { const int n = pml[8]; for (int j = 0; j < n; ++j) if (pml[j] == u.pm) slot = j; }
; #pragma unroll
;         for (int ai = 0; ai < 2; ++ai)
; #pragma unroll
;             for (int m = 0; m < 4; ++m) {
;                 const int row = row0 + ai * HALF + m * 16; bf16_t* rowp = O + (size_t)row * ldc + col0;
;                 const float r = (slot >= 0 ? tab[slot * 256 + (row - u.pm * BM)] : row_rstd(sspart, row, eps)) * sc;
.LBB0_1055:
	v_lshlrev_b32_e32 v146, 10, v146
	s_andn2_b64 vcc, exec, s[0:1]
	v_add_u32_e32 v157, v150, v146
	s_cbranch_vccnz .LBB0_1057
	ds_read_b32 v158, v157
	ds_read_b32 v230, v157 offset:64
	ds_read_b32 v231, v157 offset:128
	ds_read_b32 v232, v157 offset:192
	ds_read_b32 v233, v157 offset:512
	ds_read_b32 v234, v157 offset:576
	ds_read_b32 v235, v157 offset:640
	ds_read_b32 v252, v157 offset:704

; __device__ __forceinline__ unsigned cvt_pk_bf16(float lo, float hi) { unsigned r; asm volatile("v_cvt_pk_bf16_f32 %0, %1, %2" : "=v"(r) : "v"(lo), "v"(hi)); return r; }
; __device__ __forceinline__ float row_rstd(const float* part, int row, float eps) {
;     const f32x4* p = (const f32x4*)(part + (size_t)row * 16);
;     const f32x4 a = p[0], b = p[1], c = p[2], d = p[3];
;     const float s = ((a[0] + a[1]) + (a[2] + a[3])) + ((b[0] + b[1]) + (b[2] + b[3])) + ((c[0] + c[1]) + (c[2] + c[3])) + ((d[0] + d[1]) + (d[2] + d[3]));
;     return 1.0f / sqrtf(s * (1.0f / 1024.0f) + eps);
; }
;     __device__ __forceinline__ void operator()(const f32x4 (&acc)[2][2][4][2], const Unit& u, int wr, int wc, int fr, int fq) const {
;     ...
;             for (int m = 0; m < 4; ++m) {
;                 const int row = row0 + ai * HALF + m * 16; bf16_t* rowp = O + (size_t)row * ldc + col0;
;                 const float r = (slot >= 0 ? tab[slot * 256 + (row - u.pm * BM)] : row_rstd(sspart, row, eps)) * sc;
; #pragma unroll
;                 for (int bj = 0; bj < 2; ++bj) {
;                     f32x4 v0 = acc[ai][bj][m][0] * r, v1 = acc[ai][bj][m][1] * r;
;                     if (ACT == 1) {
; #pragma unroll
;                         for (int e = 0; e < 4; ++e) { const float a = fmaxf(v0[e], 0.f), b = fmaxf(v1[e], 0.f); v0[e] = a * a; v1[e] = b * b; }
;                     }
;                     u32x4 w; w.x = cvt_pk_bf16(v0[0], v0[1]); w.y = cvt_pk_bf16(v0[2], v0[3]); w.z = cvt_pk_bf16(v1[0], v1[1]); w.w = cvt_pk_bf16(v1[2], v1[3]);
;                     *(u32x4*)(rowp + bj * HALF) = w;
.LBB0_1059:
	s_andn2_b64 vcc, exec, s[0:1]
	s_cbranch_vccnz .LBB0_1061
	v_mov_b32_e32 v114, v230
.LBB0_1061:
	v_lshlrev_b64 v[112:113], 11, v[112:113]
	v_lshl_add_u64 v[112:113], s[14:15], 0, v[112:113]
	s_waitcnt lgkmcnt(4)
	v_mul_f32_e32 v114, 0x3db8aa3b, v114
	v_lshl_add_u64 v[112:113], v[146:147], 1, v[112:113]
	v_pk_mul_f32 v[110:111], v[110:111], v[114:115] op_sel_hi:[1,0]
	v_pk_mul_f32 v[108:109], v[108:109], v[114:115] op_sel_hi:[1,0]
	v_pk_mul_f32 v[116:117], v[106:107], v[114:115] op_sel_hi:[1,0]
	v_pk_mul_f32 v[106:107], v[104:105], v[114:115] op_sel_hi:[1,0]
	v_cvt_pk_bf16_f32 v104, v108, v109
	v_cvt_pk_bf16_f32 v105, v110, v111
	v_pk_mul_f32 v[100:101], v[100:101], v[114:115] op_sel_hi:[1,0]
	v_cvt_pk_bf16_f32 v106, v106, v107
	v_cvt_pk_bf16_f32 v107, v116, v117
	ds_bpermute_b32 v240, v253, v104
	ds_bpermute_b32 v241, v253, v105
	ds_bpermute_b32 v242, v253, v106
	ds_bpermute_b32 v243, v253, v107
	v_lshl_add_u64 v[236:237], v[112:113], 0, v[250:251]
	s_waitcnt lgkmcnt(4)
	global_store_dwordx4 v[238:239], v[244:247], off offset:256
	v_pk_mul_f32 v[102:103], v[102:103], v[114:115] op_sel_hi:[1,0]
	s_and_b64 vcc, exec, s[6:7]
	v_pk_mul_f32 v[104:105], v[98:99], v[114:115] op_sel_hi:[1,0]
	v_pk_mul_f32 v[98:99], v[96:97], v[114:115] op_sel_hi:[1,0]
	v_cvt_pk_bf16_f32 v96, v100, v101
	v_cvt_pk_bf16_f32 v97, v102, v103
	s_mov_b64 s[0:1], -1
	v_cvt_pk_bf16_f32 v98, v98, v99
	v_cvt_pk_bf16_f32 v99, v104, v105
	ds_bpermute_b32 v244, v253, v96
	ds_bpermute_b32 v245, v253, v97
	ds_bpermute_b32 v246, v253, v98
	ds_bpermute_b32 v247, v253, v99
	v_lshl_add_u64 v[238:239], v[112:113], 0, v[250:251]
	s_waitcnt lgkmcnt(4)
	global_store_dwordx4 v[236:237], v[240:243], off
	s_nop 1
	v_or_b32_e32 v96, 32, v144
	v_ashrrev_i32_e32 v97, 31, v96
	s_cbranch_vccnz .LBB0_1063
	v_lshlrev_b64 v[98:99], 6, v[96:97]
	v_lshl_add_u64 v[110:111], s[10:11], 0, v[98:99]
	global_load_dwordx4 v[98:101], v[110:111], off
	global_load_dwordx4 v[102:105], v[110:111], off offset:16
	global_load_dwordx4 v[106:109], v[110:111], off offset:32
	s_nop 0
	global_load_dwordx4 v[110:113], v[110:111], off offset:48
	s_waitcnt vmcnt(0)
	v_mov_b32_e32 v114, v99
	v_mov_b32_e32 v115, v100
	v_mov_b32_e32 v99, v101
	v_mov_b32_e32 v100, v103
	v_mov_b32_e32 v101, v104
	v_mov_b32_e32 v103, v105
	v_pk_add_f32 v[98:99], v[114:115], v[98:99]
	v_pk_add_f32 v[100:101], v[100:101], v[102:103]
	v_pk_add_f32 v[98:99], v[98:99], v[98:99] op_sel:[0,1] op_sel_hi:[1,0]
	v_pk_add_f32 v[100:101], v[100:101], v[100:101] op_sel:[0,1] op_sel_hi:[1,0]
	v_add_f32_e32 v104, v106, v107
	v_add_f32_e32 v106, v108, v109
	v_mov_b32_e32 v105, v112
	v_mov_b32_e32 v107, v113
	v_mov_b32_e32 v99, v110
	v_mov_b32_e32 v101, v111
	v_pk_add_f32 v[102:103], v[104:105], v[106:107]
	v_pk_add_f32 v[98:99], v[98:99], v[100:101]
	s_nop 0
	v_pk_add_f32 v[98:99], v[98:99], v[102:103]
	s_nop 0
	v_add_f32_e32 v98, v98, v99
	v_fmamk_f32 v98, v98, 0x3a800000, v155
	v_mul_f32_e32 v99, 0x4f800000, v98
	v_cmp_gt_f32_e32 vcc, s55, v98
	s_nop 1
	v_cndmask_b32_e32 v98, v98, v99, vcc
	v_sqrt_f32_e32 v99, v98
	s_nop 0
	v_add_u32_e32 v100, -1, v99
	v_add_u32_e32 v101, 1, v99
	v_fma_f32 v102, -v100, v99, v98
	v_fma_f32 v103, -v101, v99, v98
	v_cmp_ge_f32_e64 s[0:1], 0, v102
	s_nop 1
	v_cndmask_b32_e64 v99, v99, v100, s[0:1]
	v_cmp_lt_f32_e64 s[0:1], 0, v103
	s_nop 1
	v_cndmask_b32_e64 v99, v99, v101, s[0:1]
	v_mul_f32_e32 v100, 0x37800000, v99
	v_cndmask_b32_e32 v99, v99, v100, vcc
	v_cmp_class_f32_e32 vcc, v98, v156
	s_nop 1
	v_cndmask_b32_e32 v98, v99, v98, vcc
	v_div_scale_f32 v99, s[0:1], v98, v98, 1.0
	v_rcp_f32_e32 v100, v99
	v_div_scale_f32 v101, vcc, 1.0, v98, 1.0
	s_mov_b64 s[0:1], 0
	v_fma_f32 v102, -v99, v100, 1.0
	v_fmac_f32_e32 v100, v102, v100
	v_mul_f32_e32 v102, v101, v100
	v_fma_f32 v103, -v99, v102, v101
	v_fmac_f32_e32 v102, v103, v100
	v_fma_f32 v99, -v99, v102, v101
	v_div_fmas_f32 v99, v99, v100, v102
	v_div_fixup_f32 v98, v99, v98, 1.0
.LBB0_1063:
	s_andn2_b64 vcc, exec, s[0:1]
	s_cbranch_vccnz .LBB0_1065
	v_mov_b32_e32 v98, v231
.LBB0_1065:
	v_lshlrev_b64 v[96:97], 11, v[96:97]
	v_lshl_add_u64 v[96:97], s[14:15], 0, v[96:97]
	s_waitcnt lgkmcnt(4)
	v_mul_f32_e32 v98, 0x3db8aa3b, v98
	v_lshl_add_u64 v[96:97], v[146:147], 1, v[96:97]
	v_pk_mul_f32 v[94:95], v[94:95], v[98:99] op_sel_hi:[1,0]
	v_pk_mul_f32 v[92:93], v[92:93], v[98:99] op_sel_hi:[1,0]
	v_pk_mul_f32 v[100:101], v[90:91], v[98:99] op_sel_hi:[1,0]
	v_pk_mul_f32 v[90:91], v[88:89], v[98:99] op_sel_hi:[1,0]
	v_cvt_pk_bf16_f32 v88, v92, v93
	v_cvt_pk_bf16_f32 v89, v94, v95
	v_pk_mul_f32 v[84:85], v[84:85], v[98:99] op_sel_hi:[1,0]
	v_cvt_pk_bf16_f32 v90, v90, v91
	v_cvt_pk_bf16_f32 v91, v100, v101
	ds_bpermute_b32 v240, v253, v88
	ds_bpermute_b32 v241, v253, v89
	ds_bpermute_b32 v242, v253, v90
	ds_bpermute_b32 v243, v253, v91
	v_lshl_add_u64 v[236:237], v[96:97], 0, v[250:251]
	s_waitcnt lgkmcnt(4)
	global_store_dwordx4 v[238:239], v[244:247], off offset:256
	v_pk_mul_f32 v[86:87], v[86:87], v[98:99] op_sel_hi:[1,0]
	s_and_b64 vcc, exec, s[6:7]
	v_pk_mul_f32 v[88:89], v[82:83], v[98:99] op_sel_hi:[1,0]
	v_pk_mul_f32 v[82:83], v[80:81], v[98:99] op_sel_hi:[1,0]
	v_cvt_pk_bf16_f32 v80, v84, v85
	v_cvt_pk_bf16_f32 v81, v86, v87
	s_mov_b64 s[0:1], -1
	v_cvt_pk_bf16_f32 v82, v82, v83
	v_cvt_pk_bf16_f32 v83, v88, v89
	ds_bpermute_b32 v244, v253, v80
	ds_bpermute_b32 v245, v253, v81
	ds_bpermute_b32 v246, v253, v82
	ds_bpermute_b32 v247, v253, v83
	v_lshl_add_u64 v[238:239], v[96:97], 0, v[250:251]
	s_waitcnt lgkmcnt(4)
	global_store_dwordx4 v[236:237], v[240:243], off
	s_nop 1
	v_or_b32_e32 v80, 48, v144
	v_ashrrev_i32_e32 v81, 31, v80
	s_cbranch_vccnz .LBB0_1067
; __device__ __forceinline__ unsigned cvt_pk_bf16(float lo, float hi) { unsigned r; asm volatile("v_cvt_pk_bf16_f32 %0, %1, %2" : "=v"(r) : "v"(lo), "v"(hi)); return r; }
; __device__ __forceinline__ float row_rstd(const float* part, int row, float eps) {
;     const f32x4* p = (const f32x4*)(part + (size_t)row * 16);
;     const f32x4 a = p[0], b = p[1], c = p[2], d = p[3];
;     const float s = ((a[0] + a[1]) + (a[2] + a[3])) + ((b[0] + b[1]) + (b[2] + b[3])) + ((c[0] + c[1]) + (c[2] + c[3])) + ((d[0] + d[1]) + (d[2] + d[3]));
;     return 1.0f / sqrtf(s * (1.0f / 1024.0f) + eps);
; }
;     __device__ __forceinline__ void operator()(const f32x4 (&acc)[2][2][4][2], const Unit& u, int wr, int wc, int fr, int fq) const {
;     ...
;             for (int m = 0; m < 4; ++m) {
;                 const int row = row0 + ai * HALF + m * 16; bf16_t* rowp = O + (size_t)row * ldc + col0;
;                 const float r = (slot >= 0 ? tab[slot * 256 + (row - u.pm * BM)] : row_rstd(sspart, row, eps)) * sc;
; #pragma unroll
;                 for (int bj = 0; bj < 2; ++bj) {
;                     f32x4 v0 = acc[ai][bj][m][0] * r, v1 = acc[ai][bj][m][1] * r;
;                     if (ACT == 1) {
; #pragma unroll
;                         for (int e = 0; e < 4; ++e) { const float a = fmaxf(v0[e], 0.f), b = fmaxf(v1[e], 0.f); v0[e] = a * a; v1[e] = b * b; }
;                     }
;                     u32x4 w; w.x = cvt_pk_bf16(v0[0], v0[1]); w.y = cvt_pk_bf16(v0[2], v0[3]); w.z = cvt_pk_bf16(v1[0], v1[1]); w.w = cvt_pk_bf16(v1[2], v1[3]);
;                     *(u32x4*)(rowp + bj * HALF) = w;
	v_lshlrev_b64 v[82:83], 6, v[80:81]
	v_lshl_add_u64 v[94:95], s[10:11], 0, v[82:83]
	global_load_dwordx4 v[82:85], v[94:95], off
	global_load_dwordx4 v[86:89], v[94:95], off offset:16
	global_load_dwordx4 v[90:93], v[94:95], off offset:32
	s_nop 0
	global_load_dwordx4 v[94:97], v[94:95], off offset:48
	s_waitcnt vmcnt(0)
	v_mov_b32_e32 v98, v83
	v_mov_b32_e32 v99, v84
	v_mov_b32_e32 v83, v85
	v_mov_b32_e32 v84, v87
	v_mov_b32_e32 v85, v88
	v_mov_b32_e32 v87, v89
	v_pk_add_f32 v[82:83], v[98:99], v[82:83]
	v_pk_add_f32 v[84:85], v[84:85], v[86:87]
	v_pk_add_f32 v[82:83], v[82:83], v[82:83] op_sel:[0,1] op_sel_hi:[1,0]
	v_pk_add_f32 v[84:85], v[84:85], v[84:85] op_sel:[0,1] op_sel_hi:[1,0]
	v_add_f32_e32 v88, v90, v91
	v_add_f32_e32 v90, v92, v93
	v_mov_b32_e32 v89, v96
	v_mov_b32_e32 v91, v97
	v_mov_b32_e32 v83, v94
	v_mov_b32_e32 v85, v95
	v_pk_add_f32 v[86:87], v[88:89], v[90:91]
	v_pk_add_f32 v[82:83], v[82:83], v[84:85]
	s_nop 0
	v_pk_add_f32 v[82:83], v[82:83], v[86:87]
	s_nop 0
	v_add_f32_e32 v82, v82, v83
	v_fmamk_f32 v82, v82, 0x3a800000, v155
	v_mul_f32_e32 v83, 0x4f800000, v82
	v_cmp_gt_f32_e32 vcc, s55, v82
	s_nop 1
	v_cndmask_b32_e32 v82, v82, v83, vcc
	v_sqrt_f32_e32 v83, v82
	s_nop 0
	v_add_u32_e32 v84, -1, v83
	v_add_u32_e32 v85, 1, v83
	v_fma_f32 v86, -v84, v83, v82
	v_fma_f32 v87, -v85, v83, v82
	v_cmp_ge_f32_e64 s[0:1], 0, v86
	s_nop 1
	v_cndmask_b32_e64 v83, v83, v84, s[0:1]
	v_cmp_lt_f32_e64 s[0:1], 0, v87
	s_nop 1
	v_cndmask_b32_e64 v83, v83, v85, s[0:1]
	v_mul_f32_e32 v84, 0x37800000, v83
	v_cndmask_b32_e32 v83, v83, v84, vcc
	v_cmp_class_f32_e32 vcc, v82, v156
	s_nop 1
	v_cndmask_b32_e32 v82, v83, v82, vcc
	v_div_scale_f32 v83, s[0:1], v82, v82, 1.0
	v_rcp_f32_e32 v84, v83
	v_div_scale_f32 v85, vcc, 1.0, v82, 1.0
	s_mov_b64 s[0:1], 0
	v_fma_f32 v86, -v83, v84, 1.0
	v_fmac_f32_e32 v84, v86, v84
	v_mul_f32_e32 v86, v85, v84
	v_fma_f32 v87, -v83, v86, v85
	v_fmac_f32_e32 v86, v87, v84
	v_fma_f32 v83, -v83, v86, v85
	v_div_fmas_f32 v83, v83, v84, v86
	v_div_fixup_f32 v82, v83, v82, 1.0
.LBB0_1067:
	s_andn2_b64 vcc, exec, s[0:1]
	s_cbranch_vccnz .LBB0_1069
	v_mov_b32_e32 v82, v232
.LBB0_1069:
	v_lshlrev_b64 v[80:81], 11, v[80:81]
	v_lshl_add_u64 v[80:81], s[14:15], 0, v[80:81]
	s_waitcnt lgkmcnt(4)
	v_mul_f32_e32 v82, 0x3db8aa3b, v82
	v_lshl_add_u64 v[80:81], v[146:147], 1, v[80:81]
	v_pk_mul_f32 v[78:79], v[78:79], v[82:83] op_sel_hi:[1,0]
	v_pk_mul_f32 v[76:77], v[76:77], v[82:83] op_sel_hi:[1,0]
	v_pk_mul_f32 v[84:85], v[74:75], v[82:83] op_sel_hi:[1,0]
	v_pk_mul_f32 v[74:75], v[72:73], v[82:83] op_sel_hi:[1,0]
	v_cvt_pk_bf16_f32 v72, v76, v77
	v_cvt_pk_bf16_f32 v73, v78, v79
	v_pk_mul_f32 v[68:69], v[68:69], v[82:83] op_sel_hi:[1,0]
	v_cvt_pk_bf16_f32 v74, v74, v75
	v_cvt_pk_bf16_f32 v75, v84, v85
	ds_bpermute_b32 v240, v253, v72
	ds_bpermute_b32 v241, v253, v73
	ds_bpermute_b32 v242, v253, v74
	ds_bpermute_b32 v243, v253, v75
	v_lshl_add_u64 v[236:237], v[80:81], 0, v[250:251]
	s_waitcnt lgkmcnt(4)
	global_store_dwordx4 v[238:239], v[244:247], off offset:256
	v_pk_mul_f32 v[70:71], v[70:71], v[82:83] op_sel_hi:[1,0]
	s_and_b64 vcc, exec, s[6:7]
	v_pk_mul_f32 v[72:73], v[66:67], v[82:83] op_sel_hi:[1,0]
	v_pk_mul_f32 v[66:67], v[64:65], v[82:83] op_sel_hi:[1,0]
	v_cvt_pk_bf16_f32 v64, v68, v69
	v_cvt_pk_bf16_f32 v65, v70, v71
	s_mov_b64 s[0:1], -1
	v_cvt_pk_bf16_f32 v66, v66, v67
	v_cvt_pk_bf16_f32 v67, v72, v73
	ds_bpermute_b32 v244, v253, v64
	ds_bpermute_b32 v245, v253, v65
	ds_bpermute_b32 v246, v253, v66
	ds_bpermute_b32 v247, v253, v67
	v_lshl_add_u64 v[238:239], v[80:81], 0, v[250:251]
	s_waitcnt lgkmcnt(4)
	global_store_dwordx4 v[236:237], v[240:243], off
	s_nop 1
	v_add_u32_e32 v64, 0x80, v144
	v_ashrrev_i32_e32 v65, 31, v64
	s_cbranch_vccnz .LBB0_1071
	v_lshlrev_b64 v[66:67], 6, v[64:65]
	v_lshl_add_u64 v[78:79], s[10:11], 0, v[66:67]
	global_load_dwordx4 v[66:69], v[78:79], off
	global_load_dwordx4 v[70:73], v[78:79], off offset:16
	global_load_dwordx4 v[74:77], v[78:79], off offset:32
	s_nop 0
	global_load_dwordx4 v[78:81], v[78:79], off offset:48
	s_waitcnt vmcnt(0)
	v_mov_b32_e32 v82, v67
	v_mov_b32_e32 v83, v68
	v_mov_b32_e32 v67, v69
	v_mov_b32_e32 v68, v71
	v_mov_b32_e32 v69, v72
	v_mov_b32_e32 v71, v73
	v_pk_add_f32 v[66:67], v[82:83], v[66:67]
	v_pk_add_f32 v[68:69], v[68:69], v[70:71]
	v_pk_add_f32 v[66:67], v[66:67], v[66:67] op_sel:[0,1] op_sel_hi:[1,0]
	v_pk_add_f32 v[68:69], v[68:69], v[68:69] op_sel:[0,1] op_sel_hi:[1,0]
	v_add_f32_e32 v72, v74, v75
	v_add_f32_e32 v74, v76, v77
	v_mov_b32_e32 v73, v80
	v_mov_b32_e32 v75, v81
	v_mov_b32_e32 v67, v78
	v_mov_b32_e32 v69, v79
	v_pk_add_f32 v[70:71], v[72:73], v[74:75]
	v_pk_add_f32 v[66:67], v[66:67], v[68:69]
	s_nop 0
	v_pk_add_f32 v[66:67], v[66:67], v[70:71]
	s_nop 0
	v_add_f32_e32 v66, v66, v67
	v_fmamk_f32 v66, v66, 0x3a800000, v155
	v_mul_f32_e32 v67, 0x4f800000, v66
	v_cmp_gt_f32_e32 vcc, s55, v66
	s_nop 1
	v_cndmask_b32_e32 v66, v66, v67, vcc
	v_sqrt_f32_e32 v67, v66
	s_nop 0
	v_add_u32_e32 v68, -1, v67
	v_add_u32_e32 v69, 1, v67
	v_fma_f32 v70, -v68, v67, v66
	v_fma_f32 v71, -v69, v67, v66
	v_cmp_ge_f32_e64 s[0:1], 0, v70
	s_nop 1
	v_cndmask_b32_e64 v67, v67, v68, s[0:1]
	v_cmp_lt_f32_e64 s[0:1], 0, v71
	s_nop 1
	v_cndmask_b32_e64 v67, v67, v69, s[0:1]
	v_mul_f32_e32 v68, 0x37800000, v67
	v_cndmask_b32_e32 v67, v67, v68, vcc
	v_cmp_class_f32_e32 vcc, v66, v156
	s_nop 1
	v_cndmask_b32_e32 v66, v67, v66, vcc
	v_div_scale_f32 v67, s[0:1], v66, v66, 1.0
	v_rcp_f32_e32 v68, v67
	v_div_scale_f32 v69, vcc, 1.0, v66, 1.0
	s_mov_b64 s[0:1], 0
	v_fma_f32 v70, -v67, v68, 1.0
	v_fmac_f32_e32 v68, v70, v68
	v_mul_f32_e32 v70, v69, v68
	v_fma_f32 v71, -v67, v70, v69
	v_fmac_f32_e32 v70, v71, v68
	v_fma_f32 v67, -v67, v70, v69
	v_div_fmas_f32 v67, v67, v68, v70
	v_div_fixup_f32 v66, v67, v66, 1.0
; __device__ __forceinline__ unsigned cvt_pk_bf16(float lo, float hi) { unsigned r; asm volatile("v_cvt_pk_bf16_f32 %0, %1, %2" : "=v"(r) : "v"(lo), "v"(hi)); return r; }
; __device__ __forceinline__ float row_rstd(const float* part, int row, float eps) {
;     const f32x4* p = (const f32x4*)(part + (size_t)row * 16);
;     const f32x4 a = p[0], b = p[1], c = p[2], d = p[3];
;     const float s = ((a[0] + a[1]) + (a[2] + a[3])) + ((b[0] + b[1]) + (b[2] + b[3])) + ((c[0] + c[1]) + (c[2] + c[3])) + ((d[0] + d[1]) + (d[2] + d[3]));
;     return 1.0f / sqrtf(s * (1.0f / 1024.0f) + eps);
; }
;     __device__ __forceinline__ void operator()(const f32x4 (&acc)[2][2][4][2], const Unit& u, int wr, int wc, int fr, int fq) const {
;     ...
;             for (int m = 0; m < 4; ++m) {
;                 const int row = row0 + ai * HALF + m * 16; bf16_t* rowp = O + (size_t)row * ldc + col0;
;                 const float r = (slot >= 0 ? tab[slot * 256 + (row - u.pm * BM)] : row_rstd(sspart, row, eps)) * sc;
; #pragma unroll
;                 for (int bj = 0; bj < 2; ++bj) {
;                     f32x4 v0 = acc[ai][bj][m][0] * r, v1 = acc[ai][bj][m][1] * r;
;                     if (ACT == 1) {
; #pragma unroll
;                         for (int e = 0; e < 4; ++e) { const float a = fmaxf(v0[e], 0.f), b = fmaxf(v1[e], 0.f); v0[e] = a * a; v1[e] = b * b; }
;                     }
;                     u32x4 w; w.x = cvt_pk_bf16(v0[0], v0[1]); w.y = cvt_pk_bf16(v0[2], v0[3]); w.z = cvt_pk_bf16(v1[0], v1[1]); w.w = cvt_pk_bf16(v1[2], v1[3]);
;                     *(u32x4*)(rowp + bj * HALF) = w;
.LBB0_1071:
	s_andn2_b64 vcc, exec, s[0:1]
	s_cbranch_vccnz .LBB0_1073
	v_mov_b32_e32 v66, v233
.LBB0_1073:
	v_lshlrev_b64 v[64:65], 11, v[64:65]
	v_lshl_add_u64 v[64:65], s[14:15], 0, v[64:65]
	s_waitcnt lgkmcnt(4)
	v_mul_f32_e32 v66, 0x3db8aa3b, v66
	v_lshl_add_u64 v[64:65], v[146:147], 1, v[64:65]
	v_pk_mul_f32 v[62:63], v[62:63], v[66:67] op_sel_hi:[1,0]
	v_pk_mul_f32 v[60:61], v[60:61], v[66:67] op_sel_hi:[1,0]
	v_pk_mul_f32 v[68:69], v[58:59], v[66:67] op_sel_hi:[1,0]
	v_pk_mul_f32 v[58:59], v[56:57], v[66:67] op_sel_hi:[1,0]
	v_cvt_pk_bf16_f32 v56, v60, v61
	v_cvt_pk_bf16_f32 v57, v62, v63
	v_pk_mul_f32 v[52:53], v[52:53], v[66:67] op_sel_hi:[1,0]
	v_cvt_pk_bf16_f32 v58, v58, v59
	v_cvt_pk_bf16_f32 v59, v68, v69
	ds_bpermute_b32 v240, v253, v56
	ds_bpermute_b32 v241, v253, v57
	ds_bpermute_b32 v242, v253, v58
	ds_bpermute_b32 v243, v253, v59
	v_lshl_add_u64 v[236:237], v[64:65], 0, v[250:251]
	s_waitcnt lgkmcnt(4)
	global_store_dwordx4 v[238:239], v[244:247], off offset:256
	v_pk_mul_f32 v[54:55], v[54:55], v[66:67] op_sel_hi:[1,0]
	s_and_b64 vcc, exec, s[6:7]
	v_pk_mul_f32 v[56:57], v[50:51], v[66:67] op_sel_hi:[1,0]
	v_pk_mul_f32 v[50:51], v[48:49], v[66:67] op_sel_hi:[1,0]
	v_cvt_pk_bf16_f32 v48, v52, v53
	v_cvt_pk_bf16_f32 v49, v54, v55
	s_mov_b64 s[0:1], -1
	v_cvt_pk_bf16_f32 v50, v50, v51
	v_cvt_pk_bf16_f32 v51, v56, v57
	ds_bpermute_b32 v244, v253, v48
	ds_bpermute_b32 v245, v253, v49
	ds_bpermute_b32 v246, v253, v50
	ds_bpermute_b32 v247, v253, v51
	v_lshl_add_u64 v[238:239], v[64:65], 0, v[250:251]
	s_waitcnt lgkmcnt(4)
	global_store_dwordx4 v[236:237], v[240:243], off
	s_nop 1
	v_add_u32_e32 v48, 0x90, v144
	v_ashrrev_i32_e32 v49, 31, v48
	s_cbranch_vccnz .LBB0_1075
	v_lshlrev_b64 v[50:51], 6, v[48:49]
	v_lshl_add_u64 v[62:63], s[10:11], 0, v[50:51]
	global_load_dwordx4 v[50:53], v[62:63], off
	global_load_dwordx4 v[54:57], v[62:63], off offset:16
	global_load_dwordx4 v[58:61], v[62:63], off offset:32
	s_nop 0
	global_load_dwordx4 v[62:65], v[62:63], off offset:48
	s_waitcnt vmcnt(0)
	v_mov_b32_e32 v66, v51
	v_mov_b32_e32 v67, v52
	v_mov_b32_e32 v51, v53
	v_mov_b32_e32 v52, v55
	v_mov_b32_e32 v53, v56
	v_mov_b32_e32 v55, v57
	v_pk_add_f32 v[50:51], v[66:67], v[50:51]
	v_pk_add_f32 v[52:53], v[52:53], v[54:55]
	v_pk_add_f32 v[50:51], v[50:51], v[50:51] op_sel:[0,1] op_sel_hi:[1,0]
	v_pk_add_f32 v[52:53], v[52:53], v[52:53] op_sel:[0,1] op_sel_hi:[1,0]
	v_add_f32_e32 v56, v58, v59
	v_add_f32_e32 v58, v60, v61
	v_mov_b32_e32 v57, v64
	v_mov_b32_e32 v59, v65
	v_mov_b32_e32 v51, v62
	v_mov_b32_e32 v53, v63
	v_pk_add_f32 v[54:55], v[56:57], v[58:59]
	v_pk_add_f32 v[50:51], v[50:51], v[52:53]
	s_nop 0
	v_pk_add_f32 v[50:51], v[50:51], v[54:55]
	s_nop 0
	v_add_f32_e32 v50, v50, v51
	v_fmamk_f32 v50, v50, 0x3a800000, v155
	v_mul_f32_e32 v51, 0x4f800000, v50
	v_cmp_gt_f32_e32 vcc, s55, v50
	s_nop 1
	v_cndmask_b32_e32 v50, v50, v51, vcc
	v_sqrt_f32_e32 v51, v50
	s_nop 0
	v_add_u32_e32 v52, -1, v51
	v_add_u32_e32 v53, 1, v51
	v_fma_f32 v54, -v52, v51, v50
	v_fma_f32 v55, -v53, v51, v50
	v_cmp_ge_f32_e64 s[0:1], 0, v54
	s_nop 1
	v_cndmask_b32_e64 v51, v51, v52, s[0:1]
	v_cmp_lt_f32_e64 s[0:1], 0, v55
	s_nop 1
	v_cndmask_b32_e64 v51, v51, v53, s[0:1]
	v_mul_f32_e32 v52, 0x37800000, v51
	v_cndmask_b32_e32 v51, v51, v52, vcc
	v_cmp_class_f32_e32 vcc, v50, v156
	s_nop 1
	v_cndmask_b32_e32 v50, v51, v50, vcc
	v_div_scale_f32 v51, s[0:1], v50, v50, 1.0
	v_rcp_f32_e32 v52, v51
	v_div_scale_f32 v53, vcc, 1.0, v50, 1.0
	s_mov_b64 s[0:1], 0
	v_fma_f32 v54, -v51, v52, 1.0
	v_fmac_f32_e32 v52, v54, v52
	v_mul_f32_e32 v54, v53, v52
	v_fma_f32 v55, -v51, v54, v53
	v_fmac_f32_e32 v54, v55, v52
	v_fma_f32 v51, -v51, v54, v53
	v_div_fmas_f32 v51, v51, v52, v54
	v_div_fixup_f32 v50, v51, v50, 1.0
.LBB0_1075:
	s_andn2_b64 vcc, exec, s[0:1]
	s_cbranch_vccnz .LBB0_1077
	v_mov_b32_e32 v50, v234
.LBB0_1077:
	v_lshlrev_b64 v[48:49], 11, v[48:49]
	v_lshl_add_u64 v[48:49], s[14:15], 0, v[48:49]
	s_waitcnt lgkmcnt(4)
	v_mul_f32_e32 v50, 0x3db8aa3b, v50
	v_lshl_add_u64 v[48:49], v[146:147], 1, v[48:49]
	v_pk_mul_f32 v[46:47], v[46:47], v[50:51] op_sel_hi:[1,0]
	v_pk_mul_f32 v[44:45], v[44:45], v[50:51] op_sel_hi:[1,0]
	v_pk_mul_f32 v[52:53], v[42:43], v[50:51] op_sel_hi:[1,0]
	v_pk_mul_f32 v[42:43], v[40:41], v[50:51] op_sel_hi:[1,0]
	v_cvt_pk_bf16_f32 v40, v44, v45
	v_cvt_pk_bf16_f32 v41, v46, v47
	v_pk_mul_f32 v[36:37], v[36:37], v[50:51] op_sel_hi:[1,0]
	v_cvt_pk_bf16_f32 v42, v42, v43
	v_cvt_pk_bf16_f32 v43, v52, v53
	ds_bpermute_b32 v240, v253, v40
	ds_bpermute_b32 v241, v253, v41
	ds_bpermute_b32 v242, v253, v42
	ds_bpermute_b32 v243, v253, v43
	v_lshl_add_u64 v[236:237], v[48:49], 0, v[250:251]
	s_waitcnt lgkmcnt(4)
	global_store_dwordx4 v[238:239], v[244:247], off offset:256
	v_pk_mul_f32 v[38:39], v[38:39], v[50:51] op_sel_hi:[1,0]
	s_and_b64 vcc, exec, s[6:7]
	v_pk_mul_f32 v[40:41], v[34:35], v[50:51] op_sel_hi:[1,0]
	v_pk_mul_f32 v[34:35], v[32:33], v[50:51] op_sel_hi:[1,0]
	v_cvt_pk_bf16_f32 v32, v36, v37
	v_cvt_pk_bf16_f32 v33, v38, v39
	s_mov_b64 s[0:1], -1
	v_cvt_pk_bf16_f32 v34, v34, v35
	v_cvt_pk_bf16_f32 v35, v40, v41
	ds_bpermute_b32 v244, v253, v32
	ds_bpermute_b32 v245, v253, v33
	ds_bpermute_b32 v246, v253, v34
	ds_bpermute_b32 v247, v253, v35
	v_lshl_add_u64 v[238:239], v[48:49], 0, v[250:251]
	s_waitcnt lgkmcnt(4)
	global_store_dwordx4 v[236:237], v[240:243], off
	s_nop 1
	v_add_u32_e32 v32, 0xa0, v144
	v_ashrrev_i32_e32 v33, 31, v32
	s_cbranch_vccnz .LBB0_1079
; __device__ __forceinline__ float row_rstd(const float* part, int row, float eps) {
;     const f32x4* p = (const f32x4*)(part + (size_t)row * 16);
;     const f32x4 a = p[0], b = p[1], c = p[2], d = p[3];
;     const float s = ((a[0] + a[1]) + (a[2] + a[3])) + ((b[0] + b[1]) + (b[2] + b[3])) + ((c[0] + c[1]) + (c[2] + c[3])) + ((d[0] + d[1]) + (d[2] + d[3]));
;     return 1.0f / sqrtf(s * (1.0f / 1024.0f) + eps);
; }
;     __device__ __forceinline__ void operator()(const f32x4 (&acc)[2][2][4][2], const Unit& u, int wr, int wc, int fr, int fq) const {
;     ...
;                 const float r = (slot >= 0 ? tab[slot * 256 + (row - u.pm * BM)] : row_rstd(sspart, row, eps)) * sc;
	v_lshlrev_b64 v[34:35], 6, v[32:33]
	v_lshl_add_u64 v[46:47], s[10:11], 0, v[34:35]
	global_load_dwordx4 v[34:37], v[46:47], off
	global_load_dwordx4 v[38:41], v[46:47], off offset:16
	global_load_dwordx4 v[42:45], v[46:47], off offset:32
	s_nop 0
	global_load_dwordx4 v[46:49], v[46:47], off offset:48
	s_waitcnt vmcnt(0)
	v_mov_b32_e32 v50, v35
	v_mov_b32_e32 v51, v36
	v_mov_b32_e32 v35, v37
	v_mov_b32_e32 v36, v39
	v_mov_b32_e32 v37, v40
	v_mov_b32_e32 v39, v41
	v_pk_add_f32 v[34:35], v[50:51], v[34:35]
	v_pk_add_f32 v[36:37], v[36:37], v[38:39]
	v_pk_add_f32 v[34:35], v[34:35], v[34:35] op_sel:[0,1] op_sel_hi:[1,0]
	v_pk_add_f32 v[36:37], v[36:37], v[36:37] op_sel:[0,1] op_sel_hi:[1,0]
	v_add_f32_e32 v40, v42, v43
	v_add_f32_e32 v42, v44, v45
	v_mov_b32_e32 v41, v48
	v_mov_b32_e32 v43, v49
	v_mov_b32_e32 v35, v46
	v_mov_b32_e32 v37, v47
	v_pk_add_f32 v[38:39], v[40:41], v[42:43]
	v_pk_add_f32 v[34:35], v[34:35], v[36:37]
	s_nop 0
	v_pk_add_f32 v[34:35], v[34:35], v[38:39]
	s_nop 0
	v_add_f32_e32 v34, v34, v35
	v_fmamk_f32 v34, v34, 0x3a800000, v155
	v_mul_f32_e32 v35, 0x4f800000, v34
	v_cmp_gt_f32_e32 vcc, s55, v34
	s_nop 1
	v_cndmask_b32_e32 v34, v34, v35, vcc
	v_sqrt_f32_e32 v35, v34
	s_nop 0
	v_add_u32_e32 v36, -1, v35
	v_add_u32_e32 v37, 1, v35
	v_fma_f32 v38, -v36, v35, v34
	v_fma_f32 v39, -v37, v35, v34
	v_cmp_ge_f32_e64 s[0:1], 0, v38
	s_nop 1
	v_cndmask_b32_e64 v35, v35, v36, s[0:1]
	v_cmp_lt_f32_e64 s[0:1], 0, v39
	s_nop 1
	v_cndmask_b32_e64 v35, v35, v37, s[0:1]
	v_mul_f32_e32 v36, 0x37800000, v35
	v_cndmask_b32_e32 v35, v35, v36, vcc
	v_cmp_class_f32_e32 vcc, v34, v156
	s_nop 1
	v_cndmask_b32_e32 v34, v35, v34, vcc
	v_div_scale_f32 v35, s[0:1], v34, v34, 1.0
	v_rcp_f32_e32 v36, v35
	v_div_scale_f32 v37, vcc, 1.0, v34, 1.0
	s_mov_b64 s[0:1], 0
	v_fma_f32 v38, -v35, v36, 1.0
	v_fmac_f32_e32 v36, v38, v36
	v_mul_f32_e32 v38, v37, v36
	v_fma_f32 v39, -v35, v38, v37
	v_fmac_f32_e32 v38, v39, v36
	v_fma_f32 v35, -v35, v38, v37
	v_div_fmas_f32 v35, v35, v36, v38
	v_div_fixup_f32 v34, v35, v34, 1.0
.LBB0_1079:
	s_andn2_b64 vcc, exec, s[0:1]
	s_cbranch_vccnz .LBB0_1081
	v_mov_b32_e32 v34, v235
; __device__ __forceinline__ unsigned cvt_pk_bf16(float lo, float hi) { unsigned r; asm volatile("v_cvt_pk_bf16_f32 %0, %1, %2" : "=v"(r) : "v"(lo), "v"(hi)); return r; }
; __device__ __forceinline__ float row_rstd(const float* part, int row, float eps) {
;     const f32x4* p = (const f32x4*)(part + (size_t)row * 16);
;     const f32x4 a = p[0], b = p[1], c = p[2], d = p[3];
;     const float s = ((a[0] + a[1]) + (a[2] + a[3])) + ((b[0] + b[1]) + (b[2] + b[3])) + ((c[0] + c[1]) + (c[2] + c[3])) + ((d[0] + d[1]) + (d[2] + d[3]));
;     return 1.0f / sqrtf(s * (1.0f / 1024.0f) + eps);
; }
;     __device__ __forceinline__ void operator()(const f32x4 (&acc)[2][2][4][2], const Unit& u, int wr, int wc, int fr, int fq) const {
;     ...
;             for (int m = 0; m < 4; ++m) {
;                 const int row = row0 + ai * HALF + m * 16; bf16_t* rowp = O + (size_t)row * ldc + col0;
;                 const float r = (slot >= 0 ? tab[slot * 256 + (row - u.pm * BM)] : row_rstd(sspart, row, eps)) * sc;
; #pragma unroll
;                 for (int bj = 0; bj < 2; ++bj) {
;                     f32x4 v0 = acc[ai][bj][m][0] * r, v1 = acc[ai][bj][m][1] * r;
;                     if (ACT == 1) {
; #pragma unroll
;                         for (int e = 0; e < 4; ++e) { const float a = fmaxf(v0[e], 0.f), b = fmaxf(v1[e], 0.f); v0[e] = a * a; v1[e] = b * b; }
;                     }
;                     u32x4 w; w.x = cvt_pk_bf16(v0[0], v0[1]); w.y = cvt_pk_bf16(v0[2], v0[3]); w.z = cvt_pk_bf16(v1[0], v1[1]); w.w = cvt_pk_bf16(v1[2], v1[3]);
;                     *(u32x4*)(rowp + bj * HALF) = w;
;                 }
.LBB0_1081:
	v_lshlrev_b64 v[32:33], 11, v[32:33]
	v_lshl_add_u64 v[32:33], s[14:15], 0, v[32:33]
	s_waitcnt lgkmcnt(4)
	v_mul_f32_e32 v34, 0x3db8aa3b, v34
	v_lshl_add_u64 v[32:33], v[146:147], 1, v[32:33]
	v_pk_mul_f32 v[30:31], v[30:31], v[34:35] op_sel_hi:[1,0]
	v_pk_mul_f32 v[28:29], v[28:29], v[34:35] op_sel_hi:[1,0]
	v_pk_mul_f32 v[36:37], v[26:27], v[34:35] op_sel_hi:[1,0]
	v_pk_mul_f32 v[26:27], v[24:25], v[34:35] op_sel_hi:[1,0]
	v_cvt_pk_bf16_f32 v24, v28, v29
	v_cvt_pk_bf16_f32 v25, v30, v31
	v_pk_mul_f32 v[20:21], v[20:21], v[34:35] op_sel_hi:[1,0]
	v_cvt_pk_bf16_f32 v26, v26, v27
	v_cvt_pk_bf16_f32 v27, v36, v37
	ds_bpermute_b32 v240, v253, v24
	ds_bpermute_b32 v241, v253, v25
	ds_bpermute_b32 v242, v253, v26
	ds_bpermute_b32 v243, v253, v27
	v_lshl_add_u64 v[236:237], v[32:33], 0, v[250:251]
	s_waitcnt lgkmcnt(4)
	global_store_dwordx4 v[238:239], v[244:247], off offset:256
	v_pk_mul_f32 v[22:23], v[22:23], v[34:35] op_sel_hi:[1,0]
	s_and_b64 vcc, exec, s[6:7]
	v_pk_mul_f32 v[24:25], v[18:19], v[34:35] op_sel_hi:[1,0]
	v_pk_mul_f32 v[18:19], v[16:17], v[34:35] op_sel_hi:[1,0]
	v_cvt_pk_bf16_f32 v16, v20, v21
	v_cvt_pk_bf16_f32 v17, v22, v23
	s_mov_b64 s[0:1], -1
	v_cvt_pk_bf16_f32 v18, v18, v19
	v_cvt_pk_bf16_f32 v19, v24, v25
	ds_bpermute_b32 v244, v253, v16
	ds_bpermute_b32 v245, v253, v17
	ds_bpermute_b32 v246, v253, v18
	ds_bpermute_b32 v247, v253, v19
	v_lshl_add_u64 v[238:239], v[32:33], 0, v[250:251]
	s_waitcnt lgkmcnt(4)
	global_store_dwordx4 v[236:237], v[240:243], off
	s_nop 1
	v_add_u32_e32 v16, 0xb0, v144
	v_ashrrev_i32_e32 v17, 31, v16
	s_cbranch_vccnz .LBB0_1083
	v_lshlrev_b64 v[18:19], 6, v[16:17]
	v_lshl_add_u64 v[30:31], s[10:11], 0, v[18:19]
	global_load_dwordx4 v[18:21], v[30:31], off
	global_load_dwordx4 v[22:25], v[30:31], off offset:16
	global_load_dwordx4 v[26:29], v[30:31], off offset:32
	s_nop 0
	global_load_dwordx4 v[30:33], v[30:31], off offset:48
	s_waitcnt vmcnt(0)
	v_mov_b32_e32 v34, v19
	v_mov_b32_e32 v35, v20
	v_mov_b32_e32 v19, v21
	v_mov_b32_e32 v20, v23
	v_mov_b32_e32 v21, v24
	v_mov_b32_e32 v23, v25
	v_pk_add_f32 v[18:19], v[34:35], v[18:19]
	v_pk_add_f32 v[20:21], v[20:21], v[22:23]
	v_pk_add_f32 v[18:19], v[18:19], v[18:19] op_sel:[0,1] op_sel_hi:[1,0]
	v_pk_add_f32 v[20:21], v[20:21], v[20:21] op_sel:[0,1] op_sel_hi:[1,0]
	v_add_f32_e32 v24, v26, v27
	v_add_f32_e32 v26, v28, v29
	v_mov_b32_e32 v25, v32
	v_mov_b32_e32 v27, v33
	v_mov_b32_e32 v19, v30
	v_mov_b32_e32 v21, v31
	v_pk_add_f32 v[22:23], v[24:25], v[26:27]
	v_pk_add_f32 v[18:19], v[18:19], v[20:21]
	s_nop 0
	v_pk_add_f32 v[18:19], v[18:19], v[22:23]
	s_nop 0
	v_add_f32_e32 v18, v18, v19
	v_fmamk_f32 v18, v18, 0x3a800000, v155
	v_mul_f32_e32 v19, 0x4f800000, v18
	v_cmp_gt_f32_e32 vcc, s55, v18
	s_nop 1
	v_cndmask_b32_e32 v18, v18, v19, vcc
	v_sqrt_f32_e32 v19, v18
	s_nop 0
	v_add_u32_e32 v20, -1, v19
	v_add_u32_e32 v21, 1, v19
	v_fma_f32 v22, -v20, v19, v18
	v_fma_f32 v23, -v21, v19, v18
	v_cmp_ge_f32_e64 s[0:1], 0, v22
	s_nop 1
	v_cndmask_b32_e64 v19, v19, v20, s[0:1]
	v_cmp_lt_f32_e64 s[0:1], 0, v23
	s_nop 1
	v_cndmask_b32_e64 v19, v19, v21, s[0:1]
	v_mul_f32_e32 v20, 0x37800000, v19
	v_cndmask_b32_e32 v19, v19, v20, vcc
	v_cmp_class_f32_e32 vcc, v18, v156
	s_nop 1
	v_cndmask_b32_e32 v18, v19, v18, vcc
	v_div_scale_f32 v19, s[0:1], v18, v18, 1.0
	v_rcp_f32_e32 v20, v19
	v_div_scale_f32 v21, vcc, 1.0, v18, 1.0
	s_mov_b64 s[0:1], 0
	v_fma_f32 v22, -v19, v20, 1.0
	v_fmac_f32_e32 v20, v22, v20
	v_mul_f32_e32 v22, v21, v20
	v_fma_f32 v23, -v19, v22, v21
	v_fmac_f32_e32 v22, v23, v20
	v_fma_f32 v19, -v19, v22, v21
	v_div_fmas_f32 v19, v19, v20, v22
	v_div_fixup_f32 v18, v19, v18, 1.0
.LBB0_1083:
	s_andn2_b64 vcc, exec, s[0:1]
	s_cbranch_vccnz .LBB0_1085
	v_mov_b32_e32 v18, v252
.LBB0_1085:
	v_lshlrev_b64 v[16:17], 11, v[16:17]
	v_lshl_add_u64 v[16:17], s[14:15], 0, v[16:17]
	s_waitcnt lgkmcnt(4)
	v_mul_f32_e32 v18, 0x3db8aa3b, v18
	v_lshl_add_u64 v[16:17], v[146:147], 1, v[16:17]
	v_pk_mul_f32 v[14:15], v[14:15], v[18:19] op_sel_hi:[1,0]
	v_pk_mul_f32 v[12:13], v[12:13], v[18:19] op_sel_hi:[1,0]
	v_pk_mul_f32 v[20:21], v[10:11], v[18:19] op_sel_hi:[1,0]
	v_pk_mul_f32 v[10:11], v[8:9], v[18:19] op_sel_hi:[1,0]
	v_cvt_pk_bf16_f32 v8, v12, v13
	v_cvt_pk_bf16_f32 v9, v14, v15
	s_andn2_b64 vcc, exec, s[4:5]
	v_cvt_pk_bf16_f32 v10, v10, v11
	v_cvt_pk_bf16_f32 v11, v20, v21
	ds_bpermute_b32 v240, v253, v8
	ds_bpermute_b32 v241, v253, v9
	ds_bpermute_b32 v242, v253, v10
	ds_bpermute_b32 v243, v253, v11
	v_lshl_add_u64 v[236:237], v[16:17], 0, v[250:251]
	s_waitcnt lgkmcnt(4)
	global_store_dwordx4 v[238:239], v[244:247], off offset:256
	s_mov_b64 s[0:1], -1
	v_pk_mul_f32 v[6:7], v[6:7], v[18:19] op_sel_hi:[1,0]
	v_pk_mul_f32 v[8:9], v[2:3], v[18:19] op_sel_hi:[1,0]
	v_pk_mul_f32 v[2:3], v[0:1], v[18:19] op_sel_hi:[1,0]
	v_pk_mul_f32 v[4:5], v[4:5], v[18:19] op_sel_hi:[1,0]
	s_nop 0
	v_cvt_pk_bf16_f32 v0, v4, v5
	v_cvt_pk_bf16_f32 v1, v6, v7
	v_cvt_pk_bf16_f32 v2, v2, v3
	v_cvt_pk_bf16_f32 v3, v8, v9
	ds_bpermute_b32 v244, v253, v0
	ds_bpermute_b32 v245, v253, v1
	ds_bpermute_b32 v246, v253, v2
	ds_bpermute_b32 v247, v253, v3
	v_lshl_add_u64 v[238:239], v[16:17], 0, v[250:251]
	s_waitcnt lgkmcnt(4)
	global_store_dwordx4 v[236:237], v[240:243], off
	s_waitcnt lgkmcnt(0)
	global_store_dwordx4 v[238:239], v[244:247], off offset:256
	s_cbranch_vccnz .LBB0_1028
	s_andn2_b64 vcc, exec, s[12:13]
	s_cbranch_vccnz .LBB0_1027
	s_barrier
	s_branch .LBB0_1027

;     __device__ __forceinline__ void operator()(const f32x4 (&acc)[2][2][4][2], const Unit& u, int wr, int wc, int fr, int fq) const {
;     ...
;         int slot = -1;
;         if (tab) { const int n = pml[8]; for (int j = 0; j < n; ++j) if (pml[j] == u.pm) slot = j; }
; #pragma unroll
;         for (int ai = 0; ai < 2; ++ai)
; #pragma unroll
;             for (int m = 0; m < 4; ++m) {
;                 const int row = row0 + ai * HALF + m * 16; bf16_t* rowp = O + (size_t)row * ldc + col0;
;                 const float r = (slot >= 0 ? tab[slot * 256 + (row - u.pm * BM)] : row_rstd(sspart, row, eps)) * sc;
.LBB0_1354:
	v_lshlrev_b32_e32 v146, 10, v146
	s_andn2_b64 vcc, exec, s[0:1]
	v_add_u32_e32 v158, v151, v146
	s_cbranch_vccnz .LBB0_1356
	ds_read_b32 v148, v158
	ds_read_b32 v230, v158 offset:64
	ds_read_b32 v231, v158 offset:128
	ds_read_b32 v232, v158 offset:192
	ds_read_b32 v233, v158 offset:512
	ds_read_b32 v234, v158 offset:576
	ds_read_b32 v235, v158 offset:640
	ds_read_b32 v252, v158 offset:704

; __device__ __forceinline__ unsigned cvt_pk_bf16(float lo, float hi) { unsigned r; asm volatile("v_cvt_pk_bf16_f32 %0, %1, %2" : "=v"(r) : "v"(lo), "v"(hi)); return r; }
; __device__ __forceinline__ float row_rstd(const float* part, int row, float eps) {
;     const f32x4* p = (const f32x4*)(part + (size_t)row * 16);
;     const f32x4 a = p[0], b = p[1], c = p[2], d = p[3];
;     const float s = ((a[0] + a[1]) + (a[2] + a[3])) + ((b[0] + b[1]) + (b[2] + b[3])) + ((c[0] + c[1]) + (c[2] + c[3])) + ((d[0] + d[1]) + (d[2] + d[3]));
;     return 1.0f / sqrtf(s * (1.0f / 1024.0f) + eps);
; }
;     __device__ __forceinline__ void operator()(const f32x4 (&acc)[2][2][4][2], const Unit& u, int wr, int wc, int fr, int fq) const {
;     ...
;             for (int m = 0; m < 4; ++m) {
;                 const int row = row0 + ai * HALF + m * 16; bf16_t* rowp = O + (size_t)row * ldc + col0;
;                 const float r = (slot >= 0 ? tab[slot * 256 + (row - u.pm * BM)] : row_rstd(sspart, row, eps)) * sc;
; #pragma unroll
;                 for (int bj = 0; bj < 2; ++bj) {
;                     f32x4 v0 = acc[ai][bj][m][0] * r, v1 = acc[ai][bj][m][1] * r;
;                     if (ACT == 1) {
; #pragma unroll
;                         for (int e = 0; e < 4; ++e) { const float a = fmaxf(v0[e], 0.f), b = fmaxf(v1[e], 0.f); v0[e] = a * a; v1[e] = b * b; }
;                     }
;                     u32x4 w; w.x = cvt_pk_bf16(v0[0], v0[1]); w.y = cvt_pk_bf16(v0[2], v0[3]); w.z = cvt_pk_bf16(v1[0], v1[1]); w.w = cvt_pk_bf16(v1[2], v1[3]);
;                     *(u32x4*)(rowp + bj * HALF) = w;
;                 }
.LBB0_1360:
	s_waitcnt lgkmcnt(4)
	v_pk_mul_f32 v[104:105], v[104:105], v[114:115] op_sel_hi:[1,0]
	v_pk_mul_f32 v[108:109], v[108:109], v[114:115] op_sel_hi:[1,0]
	v_pk_mul_f32 v[106:107], v[106:107], v[114:115] op_sel_hi:[1,0]
	v_max_f32_e32 v104, 0, v104
	v_lshlrev_b64 v[112:113], 13, v[112:113]
	v_pk_mul_f32 v[110:111], v[110:111], v[114:115] op_sel_hi:[1,0]
	v_mul_f32_e32 v115, v104, v104
	v_max_f32_e32 v104, 0, v109
	v_max_f32_e32 v105, 0, v105
	v_max_f32_e32 v106, 0, v106
	v_lshl_add_u64 v[112:113], s[14:15], 0, v[112:113]
	v_max_f32_e32 v108, 0, v108
	v_mul_f32_e32 v104, v104, v104
	v_mul_f32_e32 v109, v105, v105
	v_max_f32_e32 v105, 0, v110
	v_mul_f32_e32 v110, v106, v106
	v_max_f32_e32 v106, 0, v111
	v_max_f32_e32 v107, 0, v107
	v_pk_mul_f32 v[96:97], v[96:97], v[114:115] op_sel_hi:[1,0]
	v_lshl_add_u64 v[112:113], v[146:147], 1, v[112:113]
	v_mul_f32_e32 v108, v108, v108
	v_mul_f32_e32 v105, v105, v105
	v_mul_f32_e32 v106, v106, v106
	v_mul_f32_e32 v107, v107, v107
	v_cvt_pk_bf16_f32 v104, v108, v104
	v_pk_mul_f32 v[100:101], v[100:101], v[114:115] op_sel_hi:[1,0]
	v_pk_mul_f32 v[98:99], v[98:99], v[114:115] op_sel_hi:[1,0]
	v_max_f32_e32 v96, 0, v96
	v_cvt_pk_bf16_f32 v105, v105, v106
	v_cvt_pk_bf16_f32 v106, v115, v109
	v_cvt_pk_bf16_f32 v107, v110, v107
	ds_bpermute_b32 v240, v253, v104
	ds_bpermute_b32 v241, v253, v105
	ds_bpermute_b32 v242, v253, v106
	ds_bpermute_b32 v243, v253, v107
	v_lshl_add_u64 v[236:237], v[112:113], 0, v[250:251]
	s_waitcnt lgkmcnt(4)
	global_store_dwordx4 v[238:239], v[244:247], off offset:256
	v_pk_mul_f32 v[102:103], v[102:103], v[114:115] op_sel_hi:[1,0]
	v_max_f32_e32 v97, 0, v97
	v_mul_f32_e32 v104, v96, v96
	v_max_f32_e32 v96, 0, v101
	v_max_f32_e32 v98, 0, v98
	v_max_f32_e32 v100, 0, v100
	v_mul_f32_e32 v96, v96, v96
	v_mul_f32_e32 v101, v97, v97
	v_max_f32_e32 v97, 0, v102
	v_mul_f32_e32 v102, v98, v98
	v_max_f32_e32 v98, 0, v103
	v_max_f32_e32 v99, 0, v99
	v_mul_f32_e32 v100, v100, v100
	v_mul_f32_e32 v97, v97, v97
	v_mul_f32_e32 v98, v98, v98
	v_mul_f32_e32 v99, v99, v99
	v_cvt_pk_bf16_f32 v96, v100, v96
	v_cvt_pk_bf16_f32 v97, v97, v98
	v_cvt_pk_bf16_f32 v98, v104, v101
	v_cvt_pk_bf16_f32 v99, v102, v99
	ds_bpermute_b32 v244, v253, v96
	ds_bpermute_b32 v245, v253, v97
	ds_bpermute_b32 v246, v253, v98
	ds_bpermute_b32 v247, v253, v99
	v_lshl_add_u64 v[238:239], v[112:113], 0, v[250:251]
	s_waitcnt lgkmcnt(4)
	global_store_dwordx4 v[236:237], v[240:243], off
	s_and_b64 vcc, exec, s[6:7]
	s_mov_b64 s[0:1], -1
	v_or_b32_e32 v96, 32, v144
	v_ashrrev_i32_e32 v97, 31, v96
	s_cbranch_vccnz .LBB0_1362
	v_lshlrev_b64 v[98:99], 6, v[96:97]
	v_lshl_add_u64 v[110:111], s[10:11], 0, v[98:99]
	global_load_dwordx4 v[98:101], v[110:111], off
	global_load_dwordx4 v[102:105], v[110:111], off offset:16
	global_load_dwordx4 v[106:109], v[110:111], off offset:32
	s_nop 0
	global_load_dwordx4 v[110:113], v[110:111], off offset:48
	s_waitcnt vmcnt(0)
	v_mov_b32_e32 v114, v99
	v_mov_b32_e32 v115, v100
	v_mov_b32_e32 v99, v101
	v_mov_b32_e32 v100, v103
	v_mov_b32_e32 v101, v104
	v_mov_b32_e32 v103, v105
	v_pk_add_f32 v[98:99], v[114:115], v[98:99]
	v_pk_add_f32 v[100:101], v[100:101], v[102:103]
	v_pk_add_f32 v[98:99], v[98:99], v[98:99] op_sel:[0,1] op_sel_hi:[1,0]
	v_pk_add_f32 v[100:101], v[100:101], v[100:101] op_sel:[0,1] op_sel_hi:[1,0]
	v_add_f32_e32 v104, v106, v107
	v_add_f32_e32 v106, v108, v109
	v_mov_b32_e32 v105, v112
	v_mov_b32_e32 v107, v113
	v_mov_b32_e32 v99, v110
	v_mov_b32_e32 v101, v111
	v_pk_add_f32 v[102:103], v[104:105], v[106:107]
	v_pk_add_f32 v[98:99], v[98:99], v[100:101]
	s_nop 0
	v_pk_add_f32 v[98:99], v[98:99], v[102:103]
	s_nop 0
	v_add_f32_e32 v98, v98, v99
	v_fmamk_f32 v98, v98, 0x3a800000, v156
	v_mul_f32_e32 v99, 0x4f800000, v98
	v_cmp_gt_f32_e32 vcc, s55, v98
	s_nop 1
	v_cndmask_b32_e32 v98, v98, v99, vcc
	v_sqrt_f32_e32 v99, v98
	s_nop 0
	v_add_u32_e32 v100, -1, v99
	v_add_u32_e32 v101, 1, v99
	v_fma_f32 v102, -v100, v99, v98
	v_fma_f32 v103, -v101, v99, v98
	v_cmp_ge_f32_e64 s[0:1], 0, v102
	s_nop 1
	v_cndmask_b32_e64 v99, v99, v100, s[0:1]
	v_cmp_lt_f32_e64 s[0:1], 0, v103
	s_nop 1
	v_cndmask_b32_e64 v99, v99, v101, s[0:1]
	v_mul_f32_e32 v100, 0x37800000, v99
	v_cndmask_b32_e32 v99, v99, v100, vcc
	v_cmp_class_f32_e32 vcc, v98, v157
	s_nop 1
	v_cndmask_b32_e32 v98, v99, v98, vcc
	v_div_scale_f32 v99, s[0:1], v98, v98, 1.0
	v_rcp_f32_e32 v100, v99
	v_div_scale_f32 v101, vcc, 1.0, v98, 1.0
	s_mov_b64 s[0:1], 0
	v_fma_f32 v102, -v99, v100, 1.0
	v_fmac_f32_e32 v100, v102, v100
	v_mul_f32_e32 v102, v101, v100
	v_fma_f32 v103, -v99, v102, v101
	v_fmac_f32_e32 v102, v103, v100
	v_fma_f32 v99, -v99, v102, v101
	v_div_fmas_f32 v99, v99, v100, v102
	v_div_fixup_f32 v98, v99, v98, 1.0

; __device__ __forceinline__ unsigned cvt_pk_bf16(float lo, float hi) { unsigned r; asm volatile("v_cvt_pk_bf16_f32 %0, %1, %2" : "=v"(r) : "v"(lo), "v"(hi)); return r; }
; __device__ __forceinline__ float row_rstd(const float* part, int row, float eps) {
;     const f32x4* p = (const f32x4*)(part + (size_t)row * 16);
;     const f32x4 a = p[0], b = p[1], c = p[2], d = p[3];
;     const float s = ((a[0] + a[1]) + (a[2] + a[3])) + ((b[0] + b[1]) + (b[2] + b[3])) + ((c[0] + c[1]) + (c[2] + c[3])) + ((d[0] + d[1]) + (d[2] + d[3]));
;     return 1.0f / sqrtf(s * (1.0f / 1024.0f) + eps);
; }
;     __device__ __forceinline__ void operator()(const f32x4 (&acc)[2][2][4][2], const Unit& u, int wr, int wc, int fr, int fq) const {
;     ...
;             for (int m = 0; m < 4; ++m) {
;                 const int row = row0 + ai * HALF + m * 16; bf16_t* rowp = O + (size_t)row * ldc + col0;
;                 const float r = (slot >= 0 ? tab[slot * 256 + (row - u.pm * BM)] : row_rstd(sspart, row, eps)) * sc;
; #pragma unroll
;                 for (int bj = 0; bj < 2; ++bj) {
;                     f32x4 v0 = acc[ai][bj][m][0] * r, v1 = acc[ai][bj][m][1] * r;
;                     if (ACT == 1) {
; #pragma unroll
;                         for (int e = 0; e < 4; ++e) { const float a = fmaxf(v0[e], 0.f), b = fmaxf(v1[e], 0.f); v0[e] = a * a; v1[e] = b * b; }
;                     }
;                     u32x4 w; w.x = cvt_pk_bf16(v0[0], v0[1]); w.y = cvt_pk_bf16(v0[2], v0[3]); w.z = cvt_pk_bf16(v1[0], v1[1]); w.w = cvt_pk_bf16(v1[2], v1[3]);
;                     *(u32x4*)(rowp + bj * HALF) = w;
;                 }
.LBB0_1364:
	s_waitcnt lgkmcnt(4)
	v_pk_mul_f32 v[88:89], v[88:89], v[98:99] op_sel_hi:[1,0]
	v_pk_mul_f32 v[92:93], v[92:93], v[98:99] op_sel_hi:[1,0]
	v_pk_mul_f32 v[90:91], v[90:91], v[98:99] op_sel_hi:[1,0]
	v_max_f32_e32 v88, 0, v88
	v_lshlrev_b64 v[96:97], 13, v[96:97]
	v_pk_mul_f32 v[94:95], v[94:95], v[98:99] op_sel_hi:[1,0]
	v_mul_f32_e32 v99, v88, v88
	v_max_f32_e32 v88, 0, v93
	v_max_f32_e32 v89, 0, v89
	v_max_f32_e32 v90, 0, v90
	v_lshl_add_u64 v[96:97], s[14:15], 0, v[96:97]
	v_max_f32_e32 v92, 0, v92
	v_mul_f32_e32 v88, v88, v88
	v_mul_f32_e32 v93, v89, v89
	v_max_f32_e32 v89, 0, v94
	v_mul_f32_e32 v94, v90, v90
	v_max_f32_e32 v90, 0, v95
	v_max_f32_e32 v91, 0, v91
	v_pk_mul_f32 v[80:81], v[80:81], v[98:99] op_sel_hi:[1,0]
	v_lshl_add_u64 v[96:97], v[146:147], 1, v[96:97]
	v_mul_f32_e32 v92, v92, v92
	v_mul_f32_e32 v89, v89, v89
	v_mul_f32_e32 v90, v90, v90
	v_mul_f32_e32 v91, v91, v91
	v_cvt_pk_bf16_f32 v88, v92, v88
	v_pk_mul_f32 v[84:85], v[84:85], v[98:99] op_sel_hi:[1,0]
	v_pk_mul_f32 v[82:83], v[82:83], v[98:99] op_sel_hi:[1,0]
	v_max_f32_e32 v80, 0, v80
	v_cvt_pk_bf16_f32 v89, v89, v90
	v_cvt_pk_bf16_f32 v90, v99, v93
	v_cvt_pk_bf16_f32 v91, v94, v91
	ds_bpermute_b32 v240, v253, v88
	ds_bpermute_b32 v241, v253, v89
	ds_bpermute_b32 v242, v253, v90
	ds_bpermute_b32 v243, v253, v91
	v_lshl_add_u64 v[236:237], v[96:97], 0, v[250:251]
	s_waitcnt lgkmcnt(4)
	global_store_dwordx4 v[238:239], v[244:247], off offset:256
	v_pk_mul_f32 v[86:87], v[86:87], v[98:99] op_sel_hi:[1,0]
	v_max_f32_e32 v81, 0, v81
	v_mul_f32_e32 v88, v80, v80
	v_max_f32_e32 v80, 0, v85
	v_max_f32_e32 v82, 0, v82
	v_max_f32_e32 v84, 0, v84
	v_mul_f32_e32 v80, v80, v80
	v_mul_f32_e32 v85, v81, v81
	v_max_f32_e32 v81, 0, v86
	v_mul_f32_e32 v86, v82, v82
	v_max_f32_e32 v82, 0, v87
	v_max_f32_e32 v83, 0, v83
	v_mul_f32_e32 v84, v84, v84
	v_mul_f32_e32 v81, v81, v81
	v_mul_f32_e32 v82, v82, v82
	v_mul_f32_e32 v83, v83, v83
	v_cvt_pk_bf16_f32 v80, v84, v80
	v_cvt_pk_bf16_f32 v81, v81, v82
	v_cvt_pk_bf16_f32 v82, v88, v85
	v_cvt_pk_bf16_f32 v83, v86, v83
	ds_bpermute_b32 v244, v253, v80
	ds_bpermute_b32 v245, v253, v81
	ds_bpermute_b32 v246, v253, v82
	ds_bpermute_b32 v247, v253, v83
	v_lshl_add_u64 v[238:239], v[96:97], 0, v[250:251]
	s_waitcnt lgkmcnt(4)
	global_store_dwordx4 v[236:237], v[240:243], off
	s_and_b64 vcc, exec, s[6:7]
	s_mov_b64 s[0:1], -1
	v_or_b32_e32 v80, 48, v144
	v_ashrrev_i32_e32 v81, 31, v80
	s_cbranch_vccnz .LBB0_1366
	v_lshlrev_b64 v[82:83], 6, v[80:81]
	v_lshl_add_u64 v[94:95], s[10:11], 0, v[82:83]
	global_load_dwordx4 v[82:85], v[94:95], off
	global_load_dwordx4 v[86:89], v[94:95], off offset:16
	global_load_dwordx4 v[90:93], v[94:95], off offset:32
	s_nop 0
	global_load_dwordx4 v[94:97], v[94:95], off offset:48
	s_waitcnt vmcnt(0)
	v_mov_b32_e32 v98, v83
	v_mov_b32_e32 v99, v84
	v_mov_b32_e32 v83, v85
	v_mov_b32_e32 v84, v87
	v_mov_b32_e32 v85, v88
	v_mov_b32_e32 v87, v89
	v_pk_add_f32 v[82:83], v[98:99], v[82:83]
	v_pk_add_f32 v[84:85], v[84:85], v[86:87]
	v_pk_add_f32 v[82:83], v[82:83], v[82:83] op_sel:[0,1] op_sel_hi:[1,0]
	v_pk_add_f32 v[84:85], v[84:85], v[84:85] op_sel:[0,1] op_sel_hi:[1,0]
	v_add_f32_e32 v88, v90, v91
	v_add_f32_e32 v90, v92, v93
	v_mov_b32_e32 v89, v96
	v_mov_b32_e32 v91, v97
	v_mov_b32_e32 v83, v94
	v_mov_b32_e32 v85, v95
	v_pk_add_f32 v[86:87], v[88:89], v[90:91]
	v_pk_add_f32 v[82:83], v[82:83], v[84:85]
	s_nop 0
	v_pk_add_f32 v[82:83], v[82:83], v[86:87]
	s_nop 0
	v_add_f32_e32 v82, v82, v83
	v_fmamk_f32 v82, v82, 0x3a800000, v156
	v_mul_f32_e32 v83, 0x4f800000, v82
	v_cmp_gt_f32_e32 vcc, s55, v82
	s_nop 1
	v_cndmask_b32_e32 v82, v82, v83, vcc
	v_sqrt_f32_e32 v83, v82
	s_nop 0
	v_add_u32_e32 v84, -1, v83
	v_add_u32_e32 v85, 1, v83
	v_fma_f32 v86, -v84, v83, v82
	v_fma_f32 v87, -v85, v83, v82
	v_cmp_ge_f32_e64 s[0:1], 0, v86
	s_nop 1
	v_cndmask_b32_e64 v83, v83, v84, s[0:1]
	v_cmp_lt_f32_e64 s[0:1], 0, v87
	s_nop 1
	v_cndmask_b32_e64 v83, v83, v85, s[0:1]
	v_mul_f32_e32 v84, 0x37800000, v83
	v_cndmask_b32_e32 v83, v83, v84, vcc
	v_cmp_class_f32_e32 vcc, v82, v157
	s_nop 1
	v_cndmask_b32_e32 v82, v83, v82, vcc
	v_div_scale_f32 v83, s[0:1], v82, v82, 1.0
	v_rcp_f32_e32 v84, v83
	v_div_scale_f32 v85, vcc, 1.0, v82, 1.0
	s_mov_b64 s[0:1], 0
	v_fma_f32 v86, -v83, v84, 1.0
	v_fmac_f32_e32 v84, v86, v84
	v_mul_f32_e32 v86, v85, v84
	v_fma_f32 v87, -v83, v86, v85
	v_fmac_f32_e32 v86, v87, v84
	v_fma_f32 v83, -v83, v86, v85
	v_div_fmas_f32 v83, v83, v84, v86
	v_div_fixup_f32 v82, v83, v82, 1.0

; __device__ __forceinline__ unsigned cvt_pk_bf16(float lo, float hi) { unsigned r; asm volatile("v_cvt_pk_bf16_f32 %0, %1, %2" : "=v"(r) : "v"(lo), "v"(hi)); return r; }
; __device__ __forceinline__ float row_rstd(const float* part, int row, float eps) {
;     const f32x4* p = (const f32x4*)(part + (size_t)row * 16);
;     const f32x4 a = p[0], b = p[1], c = p[2], d = p[3];
;     const float s = ((a[0] + a[1]) + (a[2] + a[3])) + ((b[0] + b[1]) + (b[2] + b[3])) + ((c[0] + c[1]) + (c[2] + c[3])) + ((d[0] + d[1]) + (d[2] + d[3]));
;     return 1.0f / sqrtf(s * (1.0f / 1024.0f) + eps);
; }
;     __device__ __forceinline__ void operator()(const f32x4 (&acc)[2][2][4][2], const Unit& u, int wr, int wc, int fr, int fq) const {
;     ...
;             for (int m = 0; m < 4; ++m) {
;                 const int row = row0 + ai * HALF + m * 16; bf16_t* rowp = O + (size_t)row * ldc + col0;
;                 const float r = (slot >= 0 ? tab[slot * 256 + (row - u.pm * BM)] : row_rstd(sspart, row, eps)) * sc;
; #pragma unroll
;                 for (int bj = 0; bj < 2; ++bj) {
;                     f32x4 v0 = acc[ai][bj][m][0] * r, v1 = acc[ai][bj][m][1] * r;
;                     if (ACT == 1) {
; #pragma unroll
;                         for (int e = 0; e < 4; ++e) { const float a = fmaxf(v0[e], 0.f), b = fmaxf(v1[e], 0.f); v0[e] = a * a; v1[e] = b * b; }
;                     }
;                     u32x4 w; w.x = cvt_pk_bf16(v0[0], v0[1]); w.y = cvt_pk_bf16(v0[2], v0[3]); w.z = cvt_pk_bf16(v1[0], v1[1]); w.w = cvt_pk_bf16(v1[2], v1[3]);
;                     *(u32x4*)(rowp + bj * HALF) = w;
;                 }
.LBB0_1368:
	s_waitcnt lgkmcnt(4)
	v_pk_mul_f32 v[72:73], v[72:73], v[82:83] op_sel_hi:[1,0]
	v_pk_mul_f32 v[76:77], v[76:77], v[82:83] op_sel_hi:[1,0]
	v_pk_mul_f32 v[74:75], v[74:75], v[82:83] op_sel_hi:[1,0]
	v_max_f32_e32 v72, 0, v72
	v_lshlrev_b64 v[80:81], 13, v[80:81]
	v_pk_mul_f32 v[78:79], v[78:79], v[82:83] op_sel_hi:[1,0]
	v_mul_f32_e32 v83, v72, v72
	v_max_f32_e32 v72, 0, v77
	v_max_f32_e32 v73, 0, v73
	v_max_f32_e32 v74, 0, v74
	v_lshl_add_u64 v[80:81], s[14:15], 0, v[80:81]
	v_max_f32_e32 v76, 0, v76
	v_mul_f32_e32 v72, v72, v72
	v_mul_f32_e32 v77, v73, v73
	v_max_f32_e32 v73, 0, v78
	v_mul_f32_e32 v78, v74, v74
	v_max_f32_e32 v74, 0, v79
	v_max_f32_e32 v75, 0, v75
	v_pk_mul_f32 v[64:65], v[64:65], v[82:83] op_sel_hi:[1,0]
	v_lshl_add_u64 v[80:81], v[146:147], 1, v[80:81]
	v_mul_f32_e32 v76, v76, v76
	v_mul_f32_e32 v73, v73, v73
	v_mul_f32_e32 v74, v74, v74
	v_mul_f32_e32 v75, v75, v75
	v_cvt_pk_bf16_f32 v72, v76, v72
	v_pk_mul_f32 v[68:69], v[68:69], v[82:83] op_sel_hi:[1,0]
	v_pk_mul_f32 v[66:67], v[66:67], v[82:83] op_sel_hi:[1,0]
	v_max_f32_e32 v64, 0, v64
	v_cvt_pk_bf16_f32 v73, v73, v74
	v_cvt_pk_bf16_f32 v74, v83, v77
	v_cvt_pk_bf16_f32 v75, v78, v75
	ds_bpermute_b32 v240, v253, v72
	ds_bpermute_b32 v241, v253, v73
	ds_bpermute_b32 v242, v253, v74
	ds_bpermute_b32 v243, v253, v75
	v_lshl_add_u64 v[236:237], v[80:81], 0, v[250:251]
	s_waitcnt lgkmcnt(4)
	global_store_dwordx4 v[238:239], v[244:247], off offset:256
	v_pk_mul_f32 v[70:71], v[70:71], v[82:83] op_sel_hi:[1,0]
	v_max_f32_e32 v65, 0, v65
	v_mul_f32_e32 v72, v64, v64
	v_max_f32_e32 v64, 0, v69
	v_max_f32_e32 v66, 0, v66
	v_max_f32_e32 v68, 0, v68
	v_mul_f32_e32 v64, v64, v64
	v_mul_f32_e32 v69, v65, v65
	v_max_f32_e32 v65, 0, v70
	v_mul_f32_e32 v70, v66, v66
	v_max_f32_e32 v66, 0, v71
	v_max_f32_e32 v67, 0, v67
	v_mul_f32_e32 v68, v68, v68
	v_mul_f32_e32 v65, v65, v65
	v_mul_f32_e32 v66, v66, v66
	v_mul_f32_e32 v67, v67, v67
	v_cvt_pk_bf16_f32 v64, v68, v64
	v_cvt_pk_bf16_f32 v65, v65, v66
	v_cvt_pk_bf16_f32 v66, v72, v69
	v_cvt_pk_bf16_f32 v67, v70, v67
	ds_bpermute_b32 v244, v253, v64
	ds_bpermute_b32 v245, v253, v65
	ds_bpermute_b32 v246, v253, v66
	ds_bpermute_b32 v247, v253, v67
	v_lshl_add_u64 v[238:239], v[80:81], 0, v[250:251]
	s_waitcnt lgkmcnt(4)
	global_store_dwordx4 v[236:237], v[240:243], off
	s_and_b64 vcc, exec, s[6:7]
	s_mov_b64 s[0:1], -1
	v_add_u32_e32 v64, 0x80, v144
	v_ashrrev_i32_e32 v65, 31, v64
	s_cbranch_vccnz .LBB0_1370
	v_lshlrev_b64 v[66:67], 6, v[64:65]
	v_lshl_add_u64 v[78:79], s[10:11], 0, v[66:67]
	global_load_dwordx4 v[66:69], v[78:79], off
	global_load_dwordx4 v[70:73], v[78:79], off offset:16
	global_load_dwordx4 v[74:77], v[78:79], off offset:32
	s_nop 0
	global_load_dwordx4 v[78:81], v[78:79], off offset:48
	s_waitcnt vmcnt(0)
	v_mov_b32_e32 v82, v67
	v_mov_b32_e32 v83, v68
	v_mov_b32_e32 v67, v69
	v_mov_b32_e32 v68, v71
	v_mov_b32_e32 v69, v72
	v_mov_b32_e32 v71, v73
	v_pk_add_f32 v[66:67], v[82:83], v[66:67]
	v_pk_add_f32 v[68:69], v[68:69], v[70:71]
	v_pk_add_f32 v[66:67], v[66:67], v[66:67] op_sel:[0,1] op_sel_hi:[1,0]
	v_pk_add_f32 v[68:69], v[68:69], v[68:69] op_sel:[0,1] op_sel_hi:[1,0]
	v_add_f32_e32 v72, v74, v75
	v_add_f32_e32 v74, v76, v77
	v_mov_b32_e32 v73, v80
	v_mov_b32_e32 v75, v81
	v_mov_b32_e32 v67, v78
	v_mov_b32_e32 v69, v79
	v_pk_add_f32 v[70:71], v[72:73], v[74:75]
	v_pk_add_f32 v[66:67], v[66:67], v[68:69]
	s_nop 0
	v_pk_add_f32 v[66:67], v[66:67], v[70:71]
	s_nop 0
	v_add_f32_e32 v66, v66, v67
	v_fmamk_f32 v66, v66, 0x3a800000, v156
	v_mul_f32_e32 v67, 0x4f800000, v66
	v_cmp_gt_f32_e32 vcc, s55, v66
	s_nop 1
	v_cndmask_b32_e32 v66, v66, v67, vcc
	v_sqrt_f32_e32 v67, v66
	s_nop 0
	v_add_u32_e32 v68, -1, v67
	v_add_u32_e32 v69, 1, v67
	v_fma_f32 v70, -v68, v67, v66
	v_fma_f32 v71, -v69, v67, v66
	v_cmp_ge_f32_e64 s[0:1], 0, v70
	s_nop 1
	v_cndmask_b32_e64 v67, v67, v68, s[0:1]
	v_cmp_lt_f32_e64 s[0:1], 0, v71
	s_nop 1
	v_cndmask_b32_e64 v67, v67, v69, s[0:1]
	v_mul_f32_e32 v68, 0x37800000, v67
	v_cndmask_b32_e32 v67, v67, v68, vcc
	v_cmp_class_f32_e32 vcc, v66, v157
	s_nop 1
	v_cndmask_b32_e32 v66, v67, v66, vcc
	v_div_scale_f32 v67, s[0:1], v66, v66, 1.0
	v_rcp_f32_e32 v68, v67
	v_div_scale_f32 v69, vcc, 1.0, v66, 1.0
	s_mov_b64 s[0:1], 0
	v_fma_f32 v70, -v67, v68, 1.0
	v_fmac_f32_e32 v68, v70, v68
	v_mul_f32_e32 v70, v69, v68
	v_fma_f32 v71, -v67, v70, v69
	v_fmac_f32_e32 v70, v71, v68
	v_fma_f32 v67, -v67, v70, v69
	v_div_fmas_f32 v67, v67, v68, v70
	v_div_fixup_f32 v66, v67, v66, 1.0

; __device__ __forceinline__ unsigned cvt_pk_bf16(float lo, float hi) { unsigned r; asm volatile("v_cvt_pk_bf16_f32 %0, %1, %2" : "=v"(r) : "v"(lo), "v"(hi)); return r; }
; __device__ __forceinline__ float row_rstd(const float* part, int row, float eps) {
;     const f32x4* p = (const f32x4*)(part + (size_t)row * 16);
;     const f32x4 a = p[0], b = p[1], c = p[2], d = p[3];
;     const float s = ((a[0] + a[1]) + (a[2] + a[3])) + ((b[0] + b[1]) + (b[2] + b[3])) + ((c[0] + c[1]) + (c[2] + c[3])) + ((d[0] + d[1]) + (d[2] + d[3]));
;     return 1.0f / sqrtf(s * (1.0f / 1024.0f) + eps);
; }
;     __device__ __forceinline__ void operator()(const f32x4 (&acc)[2][2][4][2], const Unit& u, int wr, int wc, int fr, int fq) const {
;     ...
;             for (int m = 0; m < 4; ++m) {
;                 const int row = row0 + ai * HALF + m * 16; bf16_t* rowp = O + (size_t)row * ldc + col0;
;                 const float r = (slot >= 0 ? tab[slot * 256 + (row - u.pm * BM)] : row_rstd(sspart, row, eps)) * sc;
; #pragma unroll
;                 for (int bj = 0; bj < 2; ++bj) {
;                     f32x4 v0 = acc[ai][bj][m][0] * r, v1 = acc[ai][bj][m][1] * r;
;                     if (ACT == 1) {
; #pragma unroll
;                         for (int e = 0; e < 4; ++e) { const float a = fmaxf(v0[e], 0.f), b = fmaxf(v1[e], 0.f); v0[e] = a * a; v1[e] = b * b; }
;                     }
;                     u32x4 w; w.x = cvt_pk_bf16(v0[0], v0[1]); w.y = cvt_pk_bf16(v0[2], v0[3]); w.z = cvt_pk_bf16(v1[0], v1[1]); w.w = cvt_pk_bf16(v1[2], v1[3]);
;                     *(u32x4*)(rowp + bj * HALF) = w;
;                 }
.LBB0_1372:
	s_waitcnt lgkmcnt(4)
	v_pk_mul_f32 v[56:57], v[56:57], v[66:67] op_sel_hi:[1,0]
	v_pk_mul_f32 v[60:61], v[60:61], v[66:67] op_sel_hi:[1,0]
	v_pk_mul_f32 v[58:59], v[58:59], v[66:67] op_sel_hi:[1,0]
	v_max_f32_e32 v56, 0, v56
	v_lshlrev_b64 v[64:65], 13, v[64:65]
	v_pk_mul_f32 v[62:63], v[62:63], v[66:67] op_sel_hi:[1,0]
	v_mul_f32_e32 v67, v56, v56
	v_max_f32_e32 v56, 0, v61
	v_max_f32_e32 v57, 0, v57
	v_max_f32_e32 v58, 0, v58
	v_lshl_add_u64 v[64:65], s[14:15], 0, v[64:65]
	v_max_f32_e32 v60, 0, v60
	v_mul_f32_e32 v56, v56, v56
	v_mul_f32_e32 v61, v57, v57
	v_max_f32_e32 v57, 0, v62
	v_mul_f32_e32 v62, v58, v58
	v_max_f32_e32 v58, 0, v63
	v_max_f32_e32 v59, 0, v59
	v_pk_mul_f32 v[48:49], v[48:49], v[66:67] op_sel_hi:[1,0]
	v_lshl_add_u64 v[64:65], v[146:147], 1, v[64:65]
	v_mul_f32_e32 v60, v60, v60
	v_mul_f32_e32 v57, v57, v57
	v_mul_f32_e32 v58, v58, v58
	v_mul_f32_e32 v59, v59, v59
	v_cvt_pk_bf16_f32 v56, v60, v56
	v_pk_mul_f32 v[52:53], v[52:53], v[66:67] op_sel_hi:[1,0]
	v_pk_mul_f32 v[50:51], v[50:51], v[66:67] op_sel_hi:[1,0]
	v_max_f32_e32 v48, 0, v48
	v_cvt_pk_bf16_f32 v57, v57, v58
	v_cvt_pk_bf16_f32 v58, v67, v61
	v_cvt_pk_bf16_f32 v59, v62, v59
	ds_bpermute_b32 v240, v253, v56
	ds_bpermute_b32 v241, v253, v57
	ds_bpermute_b32 v242, v253, v58
	ds_bpermute_b32 v243, v253, v59
	v_lshl_add_u64 v[236:237], v[64:65], 0, v[250:251]
	s_waitcnt lgkmcnt(4)
	global_store_dwordx4 v[238:239], v[244:247], off offset:256
	v_pk_mul_f32 v[54:55], v[54:55], v[66:67] op_sel_hi:[1,0]
	v_max_f32_e32 v49, 0, v49
	v_mul_f32_e32 v56, v48, v48
	v_max_f32_e32 v48, 0, v53
	v_max_f32_e32 v50, 0, v50
	v_max_f32_e32 v52, 0, v52
	v_mul_f32_e32 v48, v48, v48
	v_mul_f32_e32 v53, v49, v49
	v_max_f32_e32 v49, 0, v54
	v_mul_f32_e32 v54, v50, v50
	v_max_f32_e32 v50, 0, v55
	v_max_f32_e32 v51, 0, v51
	v_mul_f32_e32 v52, v52, v52
	v_mul_f32_e32 v49, v49, v49
	v_mul_f32_e32 v50, v50, v50
	v_mul_f32_e32 v51, v51, v51
	v_cvt_pk_bf16_f32 v48, v52, v48
	v_cvt_pk_bf16_f32 v49, v49, v50
	v_cvt_pk_bf16_f32 v50, v56, v53
	v_cvt_pk_bf16_f32 v51, v54, v51
	ds_bpermute_b32 v244, v253, v48
	ds_bpermute_b32 v245, v253, v49
	ds_bpermute_b32 v246, v253, v50
	ds_bpermute_b32 v247, v253, v51
	v_lshl_add_u64 v[238:239], v[64:65], 0, v[250:251]
	s_waitcnt lgkmcnt(4)
	global_store_dwordx4 v[236:237], v[240:243], off
	s_and_b64 vcc, exec, s[6:7]
	s_mov_b64 s[0:1], -1
	v_add_u32_e32 v48, 0x90, v144
	v_ashrrev_i32_e32 v49, 31, v48
	s_cbranch_vccnz .LBB0_1374
	v_lshlrev_b64 v[50:51], 6, v[48:49]
	v_lshl_add_u64 v[62:63], s[10:11], 0, v[50:51]
	global_load_dwordx4 v[50:53], v[62:63], off
	global_load_dwordx4 v[54:57], v[62:63], off offset:16
	global_load_dwordx4 v[58:61], v[62:63], off offset:32
	s_nop 0
	global_load_dwordx4 v[62:65], v[62:63], off offset:48
	s_waitcnt vmcnt(0)
	v_mov_b32_e32 v66, v51
	v_mov_b32_e32 v67, v52
	v_mov_b32_e32 v51, v53
	v_mov_b32_e32 v52, v55
	v_mov_b32_e32 v53, v56
	v_mov_b32_e32 v55, v57
	v_pk_add_f32 v[50:51], v[66:67], v[50:51]
	v_pk_add_f32 v[52:53], v[52:53], v[54:55]
	v_pk_add_f32 v[50:51], v[50:51], v[50:51] op_sel:[0,1] op_sel_hi:[1,0]
	v_pk_add_f32 v[52:53], v[52:53], v[52:53] op_sel:[0,1] op_sel_hi:[1,0]
	v_add_f32_e32 v56, v58, v59
	v_add_f32_e32 v58, v60, v61
	v_mov_b32_e32 v57, v64
	v_mov_b32_e32 v59, v65
	v_mov_b32_e32 v51, v62
	v_mov_b32_e32 v53, v63
	v_pk_add_f32 v[54:55], v[56:57], v[58:59]
	v_pk_add_f32 v[50:51], v[50:51], v[52:53]
	s_nop 0
	v_pk_add_f32 v[50:51], v[50:51], v[54:55]
	s_nop 0
	v_add_f32_e32 v50, v50, v51
	v_fmamk_f32 v50, v50, 0x3a800000, v156
	v_mul_f32_e32 v51, 0x4f800000, v50
	v_cmp_gt_f32_e32 vcc, s55, v50
	s_nop 1
	v_cndmask_b32_e32 v50, v50, v51, vcc
	v_sqrt_f32_e32 v51, v50
	s_nop 0
	v_add_u32_e32 v52, -1, v51
	v_add_u32_e32 v53, 1, v51
	v_fma_f32 v54, -v52, v51, v50
	v_fma_f32 v55, -v53, v51, v50
	v_cmp_ge_f32_e64 s[0:1], 0, v54
	s_nop 1
	v_cndmask_b32_e64 v51, v51, v52, s[0:1]
	v_cmp_lt_f32_e64 s[0:1], 0, v55
	s_nop 1
	v_cndmask_b32_e64 v51, v51, v53, s[0:1]
	v_mul_f32_e32 v52, 0x37800000, v51
	v_cndmask_b32_e32 v51, v51, v52, vcc
	v_cmp_class_f32_e32 vcc, v50, v157
	s_nop 1
	v_cndmask_b32_e32 v50, v51, v50, vcc
	v_div_scale_f32 v51, s[0:1], v50, v50, 1.0
	v_rcp_f32_e32 v52, v51
	v_div_scale_f32 v53, vcc, 1.0, v50, 1.0
	s_mov_b64 s[0:1], 0
	v_fma_f32 v54, -v51, v52, 1.0
	v_fmac_f32_e32 v52, v54, v52
	v_mul_f32_e32 v54, v53, v52
	v_fma_f32 v55, -v51, v54, v53
	v_fmac_f32_e32 v54, v55, v52
	v_fma_f32 v51, -v51, v54, v53
	v_div_fmas_f32 v51, v51, v52, v54
	v_div_fixup_f32 v50, v51, v50, 1.0

; __device__ __forceinline__ unsigned cvt_pk_bf16(float lo, float hi) { unsigned r; asm volatile("v_cvt_pk_bf16_f32 %0, %1, %2" : "=v"(r) : "v"(lo), "v"(hi)); return r; }
; __device__ __forceinline__ float row_rstd(const float* part, int row, float eps) {
;     const f32x4* p = (const f32x4*)(part + (size_t)row * 16);
;     const f32x4 a = p[0], b = p[1], c = p[2], d = p[3];
;     const float s = ((a[0] + a[1]) + (a[2] + a[3])) + ((b[0] + b[1]) + (b[2] + b[3])) + ((c[0] + c[1]) + (c[2] + c[3])) + ((d[0] + d[1]) + (d[2] + d[3]));
;     return 1.0f / sqrtf(s * (1.0f / 1024.0f) + eps);
; }
;     __device__ __forceinline__ void operator()(const f32x4 (&acc)[2][2][4][2], const Unit& u, int wr, int wc, int fr, int fq) const {
;     ...
;             for (int m = 0; m < 4; ++m) {
;                 const int row = row0 + ai * HALF + m * 16; bf16_t* rowp = O + (size_t)row * ldc + col0;
;                 const float r = (slot >= 0 ? tab[slot * 256 + (row - u.pm * BM)] : row_rstd(sspart, row, eps)) * sc;
; #pragma unroll
;                 for (int bj = 0; bj < 2; ++bj) {
;                     f32x4 v0 = acc[ai][bj][m][0] * r, v1 = acc[ai][bj][m][1] * r;
;                     if (ACT == 1) {
; #pragma unroll
;                         for (int e = 0; e < 4; ++e) { const float a = fmaxf(v0[e], 0.f), b = fmaxf(v1[e], 0.f); v0[e] = a * a; v1[e] = b * b; }
;                     }
;                     u32x4 w; w.x = cvt_pk_bf16(v0[0], v0[1]); w.y = cvt_pk_bf16(v0[2], v0[3]); w.z = cvt_pk_bf16(v1[0], v1[1]); w.w = cvt_pk_bf16(v1[2], v1[3]);
;                     *(u32x4*)(rowp + bj * HALF) = w;
;                 }
.LBB0_1376:
	s_waitcnt lgkmcnt(4)
	v_pk_mul_f32 v[40:41], v[40:41], v[50:51] op_sel_hi:[1,0]
	v_pk_mul_f32 v[44:45], v[44:45], v[50:51] op_sel_hi:[1,0]
	v_pk_mul_f32 v[42:43], v[42:43], v[50:51] op_sel_hi:[1,0]
	v_max_f32_e32 v40, 0, v40
	v_lshlrev_b64 v[48:49], 13, v[48:49]
	v_pk_mul_f32 v[46:47], v[46:47], v[50:51] op_sel_hi:[1,0]
	v_mul_f32_e32 v51, v40, v40
	v_max_f32_e32 v40, 0, v45
	v_max_f32_e32 v41, 0, v41
	v_max_f32_e32 v42, 0, v42
	v_lshl_add_u64 v[48:49], s[14:15], 0, v[48:49]
	v_max_f32_e32 v44, 0, v44
	v_mul_f32_e32 v40, v40, v40
	v_mul_f32_e32 v45, v41, v41
	v_max_f32_e32 v41, 0, v46
	v_mul_f32_e32 v46, v42, v42
	v_max_f32_e32 v42, 0, v47
	v_max_f32_e32 v43, 0, v43
	v_pk_mul_f32 v[32:33], v[32:33], v[50:51] op_sel_hi:[1,0]
	v_lshl_add_u64 v[48:49], v[146:147], 1, v[48:49]
	v_mul_f32_e32 v44, v44, v44
	v_mul_f32_e32 v41, v41, v41
	v_mul_f32_e32 v42, v42, v42
	v_mul_f32_e32 v43, v43, v43
	v_cvt_pk_bf16_f32 v40, v44, v40
	v_pk_mul_f32 v[36:37], v[36:37], v[50:51] op_sel_hi:[1,0]
	v_pk_mul_f32 v[34:35], v[34:35], v[50:51] op_sel_hi:[1,0]
	v_max_f32_e32 v32, 0, v32
	v_cvt_pk_bf16_f32 v41, v41, v42
	v_cvt_pk_bf16_f32 v42, v51, v45
	v_cvt_pk_bf16_f32 v43, v46, v43
	ds_bpermute_b32 v240, v253, v40
	ds_bpermute_b32 v241, v253, v41
	ds_bpermute_b32 v242, v253, v42
	ds_bpermute_b32 v243, v253, v43
	v_lshl_add_u64 v[236:237], v[48:49], 0, v[250:251]
	s_waitcnt lgkmcnt(4)
	global_store_dwordx4 v[238:239], v[244:247], off offset:256
	v_pk_mul_f32 v[38:39], v[38:39], v[50:51] op_sel_hi:[1,0]
	v_max_f32_e32 v33, 0, v33
	v_mul_f32_e32 v40, v32, v32
	v_max_f32_e32 v32, 0, v37
	v_max_f32_e32 v34, 0, v34
	v_max_f32_e32 v36, 0, v36
	v_mul_f32_e32 v32, v32, v32
	v_mul_f32_e32 v37, v33, v33
	v_max_f32_e32 v33, 0, v38
	v_mul_f32_e32 v38, v34, v34
	v_max_f32_e32 v34, 0, v39
	v_max_f32_e32 v35, 0, v35
	v_mul_f32_e32 v36, v36, v36
	v_mul_f32_e32 v33, v33, v33
	v_mul_f32_e32 v34, v34, v34
	v_mul_f32_e32 v35, v35, v35
	v_cvt_pk_bf16_f32 v32, v36, v32
	v_cvt_pk_bf16_f32 v33, v33, v34
	v_cvt_pk_bf16_f32 v34, v40, v37
	v_cvt_pk_bf16_f32 v35, v38, v35
	ds_bpermute_b32 v244, v253, v32
	ds_bpermute_b32 v245, v253, v33
	ds_bpermute_b32 v246, v253, v34
	ds_bpermute_b32 v247, v253, v35
	v_lshl_add_u64 v[238:239], v[48:49], 0, v[250:251]
	s_waitcnt lgkmcnt(4)
	global_store_dwordx4 v[236:237], v[240:243], off
	s_and_b64 vcc, exec, s[6:7]
	s_mov_b64 s[0:1], -1
	v_add_u32_e32 v32, 0xa0, v144
	v_ashrrev_i32_e32 v33, 31, v32
	s_cbranch_vccnz .LBB0_1378
	v_lshlrev_b64 v[34:35], 6, v[32:33]
	v_lshl_add_u64 v[46:47], s[10:11], 0, v[34:35]
	global_load_dwordx4 v[34:37], v[46:47], off
	global_load_dwordx4 v[38:41], v[46:47], off offset:16
	global_load_dwordx4 v[42:45], v[46:47], off offset:32
	s_nop 0
	global_load_dwordx4 v[46:49], v[46:47], off offset:48
	s_waitcnt vmcnt(0)
	v_mov_b32_e32 v50, v35
	v_mov_b32_e32 v51, v36
	v_mov_b32_e32 v35, v37
	v_mov_b32_e32 v36, v39
	v_mov_b32_e32 v37, v40
	v_mov_b32_e32 v39, v41
	v_pk_add_f32 v[34:35], v[50:51], v[34:35]
	v_pk_add_f32 v[36:37], v[36:37], v[38:39]
	v_pk_add_f32 v[34:35], v[34:35], v[34:35] op_sel:[0,1] op_sel_hi:[1,0]
	v_pk_add_f32 v[36:37], v[36:37], v[36:37] op_sel:[0,1] op_sel_hi:[1,0]
	v_add_f32_e32 v40, v42, v43
	v_add_f32_e32 v42, v44, v45
	v_mov_b32_e32 v41, v48
	v_mov_b32_e32 v43, v49
	v_mov_b32_e32 v35, v46
	v_mov_b32_e32 v37, v47
	v_pk_add_f32 v[38:39], v[40:41], v[42:43]
	v_pk_add_f32 v[34:35], v[34:35], v[36:37]
	s_nop 0
	v_pk_add_f32 v[34:35], v[34:35], v[38:39]
	s_nop 0
	v_add_f32_e32 v34, v34, v35
	v_fmamk_f32 v34, v34, 0x3a800000, v156
	v_mul_f32_e32 v35, 0x4f800000, v34
	v_cmp_gt_f32_e32 vcc, s55, v34
	s_nop 1
	v_cndmask_b32_e32 v34, v34, v35, vcc
	v_sqrt_f32_e32 v35, v34
	s_nop 0
	v_add_u32_e32 v36, -1, v35
	v_add_u32_e32 v37, 1, v35
	v_fma_f32 v38, -v36, v35, v34
	v_fma_f32 v39, -v37, v35, v34
	v_cmp_ge_f32_e64 s[0:1], 0, v38
	s_nop 1
	v_cndmask_b32_e64 v35, v35, v36, s[0:1]
	v_cmp_lt_f32_e64 s[0:1], 0, v39
	s_nop 1
	v_cndmask_b32_e64 v35, v35, v37, s[0:1]
	v_mul_f32_e32 v36, 0x37800000, v35
	v_cndmask_b32_e32 v35, v35, v36, vcc
	v_cmp_class_f32_e32 vcc, v34, v157
	s_nop 1
	v_cndmask_b32_e32 v34, v35, v34, vcc
	v_div_scale_f32 v35, s[0:1], v34, v34, 1.0
	v_rcp_f32_e32 v36, v35
	v_div_scale_f32 v37, vcc, 1.0, v34, 1.0
	s_mov_b64 s[0:1], 0
	v_fma_f32 v38, -v35, v36, 1.0
	v_fmac_f32_e32 v36, v38, v36
	v_mul_f32_e32 v38, v37, v36
	v_fma_f32 v39, -v35, v38, v37
	v_fmac_f32_e32 v38, v39, v36
	v_fma_f32 v35, -v35, v38, v37
	v_div_fmas_f32 v35, v35, v36, v38
	v_div_fixup_f32 v34, v35, v34, 1.0

; __device__ __forceinline__ unsigned cvt_pk_bf16(float lo, float hi) { unsigned r; asm volatile("v_cvt_pk_bf16_f32 %0, %1, %2" : "=v"(r) : "v"(lo), "v"(hi)); return r; }
; __device__ __forceinline__ float row_rstd(const float* part, int row, float eps) {
;     const f32x4* p = (const f32x4*)(part + (size_t)row * 16);
;     const f32x4 a = p[0], b = p[1], c = p[2], d = p[3];
;     const float s = ((a[0] + a[1]) + (a[2] + a[3])) + ((b[0] + b[1]) + (b[2] + b[3])) + ((c[0] + c[1]) + (c[2] + c[3])) + ((d[0] + d[1]) + (d[2] + d[3]));
;     return 1.0f / sqrtf(s * (1.0f / 1024.0f) + eps);
; }
;     __device__ __forceinline__ void operator()(const f32x4 (&acc)[2][2][4][2], const Unit& u, int wr, int wc, int fr, int fq) const {
;     ...
;             for (int m = 0; m < 4; ++m) {
;                 const int row = row0 + ai * HALF + m * 16; bf16_t* rowp = O + (size_t)row * ldc + col0;
;                 const float r = (slot >= 0 ? tab[slot * 256 + (row - u.pm * BM)] : row_rstd(sspart, row, eps)) * sc;
; #pragma unroll
;                 for (int bj = 0; bj < 2; ++bj) {
;                     f32x4 v0 = acc[ai][bj][m][0] * r, v1 = acc[ai][bj][m][1] * r;
;                     if (ACT == 1) {
; #pragma unroll
;                         for (int e = 0; e < 4; ++e) { const float a = fmaxf(v0[e], 0.f), b = fmaxf(v1[e], 0.f); v0[e] = a * a; v1[e] = b * b; }
;                     }
;                     u32x4 w; w.x = cvt_pk_bf16(v0[0], v0[1]); w.y = cvt_pk_bf16(v0[2], v0[3]); w.z = cvt_pk_bf16(v1[0], v1[1]); w.w = cvt_pk_bf16(v1[2], v1[3]);
;                     *(u32x4*)(rowp + bj * HALF) = w;
;                 }
.LBB0_1380:
	s_waitcnt lgkmcnt(4)
	v_pk_mul_f32 v[24:25], v[24:25], v[34:35] op_sel_hi:[1,0]
	v_pk_mul_f32 v[28:29], v[28:29], v[34:35] op_sel_hi:[1,0]
	v_pk_mul_f32 v[26:27], v[26:27], v[34:35] op_sel_hi:[1,0]
	v_max_f32_e32 v24, 0, v24
	v_lshlrev_b64 v[32:33], 13, v[32:33]
	v_pk_mul_f32 v[30:31], v[30:31], v[34:35] op_sel_hi:[1,0]
	v_mul_f32_e32 v35, v24, v24
	v_max_f32_e32 v24, 0, v29
	v_max_f32_e32 v25, 0, v25
	v_max_f32_e32 v26, 0, v26
	v_lshl_add_u64 v[32:33], s[14:15], 0, v[32:33]
	v_max_f32_e32 v28, 0, v28
	v_mul_f32_e32 v24, v24, v24
	v_mul_f32_e32 v29, v25, v25
	v_max_f32_e32 v25, 0, v30
	v_mul_f32_e32 v30, v26, v26
	v_max_f32_e32 v26, 0, v31
	v_max_f32_e32 v27, 0, v27
	v_pk_mul_f32 v[16:17], v[16:17], v[34:35] op_sel_hi:[1,0]
	v_lshl_add_u64 v[32:33], v[146:147], 1, v[32:33]
	v_mul_f32_e32 v28, v28, v28
	v_mul_f32_e32 v25, v25, v25
	v_mul_f32_e32 v26, v26, v26
	v_mul_f32_e32 v27, v27, v27
	v_cvt_pk_bf16_f32 v24, v28, v24
	v_pk_mul_f32 v[20:21], v[20:21], v[34:35] op_sel_hi:[1,0]
	v_pk_mul_f32 v[18:19], v[18:19], v[34:35] op_sel_hi:[1,0]
	v_max_f32_e32 v16, 0, v16
	v_cvt_pk_bf16_f32 v25, v25, v26
	v_cvt_pk_bf16_f32 v26, v35, v29
	v_cvt_pk_bf16_f32 v27, v30, v27
	ds_bpermute_b32 v240, v253, v24
	ds_bpermute_b32 v241, v253, v25
	ds_bpermute_b32 v242, v253, v26
	ds_bpermute_b32 v243, v253, v27
	v_lshl_add_u64 v[236:237], v[32:33], 0, v[250:251]
	s_waitcnt lgkmcnt(4)
	global_store_dwordx4 v[238:239], v[244:247], off offset:256
	v_pk_mul_f32 v[22:23], v[22:23], v[34:35] op_sel_hi:[1,0]
	v_max_f32_e32 v17, 0, v17
	v_mul_f32_e32 v24, v16, v16
	v_max_f32_e32 v16, 0, v21
	v_max_f32_e32 v18, 0, v18
	v_max_f32_e32 v20, 0, v20
	v_mul_f32_e32 v16, v16, v16
	v_mul_f32_e32 v21, v17, v17
	v_max_f32_e32 v17, 0, v22
	v_mul_f32_e32 v22, v18, v18
	v_max_f32_e32 v18, 0, v23
	v_max_f32_e32 v19, 0, v19
	v_mul_f32_e32 v20, v20, v20
	v_mul_f32_e32 v17, v17, v17
	v_mul_f32_e32 v18, v18, v18
	v_mul_f32_e32 v19, v19, v19
	v_cvt_pk_bf16_f32 v16, v20, v16
	v_cvt_pk_bf16_f32 v17, v17, v18
	v_cvt_pk_bf16_f32 v18, v24, v21
	v_cvt_pk_bf16_f32 v19, v22, v19
	ds_bpermute_b32 v244, v253, v16
	ds_bpermute_b32 v245, v253, v17
	ds_bpermute_b32 v246, v253, v18
	ds_bpermute_b32 v247, v253, v19
	v_lshl_add_u64 v[238:239], v[32:33], 0, v[250:251]
	s_waitcnt lgkmcnt(4)
	global_store_dwordx4 v[236:237], v[240:243], off
	s_and_b64 vcc, exec, s[6:7]
	s_mov_b64 s[0:1], -1
	v_add_u32_e32 v16, 0xb0, v144
	v_ashrrev_i32_e32 v17, 31, v16
	s_cbranch_vccnz .LBB0_1382
	v_lshlrev_b64 v[18:19], 6, v[16:17]
	v_lshl_add_u64 v[30:31], s[10:11], 0, v[18:19]
	global_load_dwordx4 v[18:21], v[30:31], off
	global_load_dwordx4 v[22:25], v[30:31], off offset:16
	global_load_dwordx4 v[26:29], v[30:31], off offset:32
	s_nop 0
	global_load_dwordx4 v[30:33], v[30:31], off offset:48
	s_waitcnt vmcnt(0)
	v_mov_b32_e32 v34, v19
	v_mov_b32_e32 v35, v20
	v_mov_b32_e32 v19, v21
	v_mov_b32_e32 v20, v23
	v_mov_b32_e32 v21, v24
	v_mov_b32_e32 v23, v25
	v_pk_add_f32 v[18:19], v[34:35], v[18:19]
	v_pk_add_f32 v[20:21], v[20:21], v[22:23]
	v_pk_add_f32 v[18:19], v[18:19], v[18:19] op_sel:[0,1] op_sel_hi:[1,0]
	v_pk_add_f32 v[20:21], v[20:21], v[20:21] op_sel:[0,1] op_sel_hi:[1,0]
	v_add_f32_e32 v24, v26, v27
	v_add_f32_e32 v26, v28, v29
	v_mov_b32_e32 v25, v32
	v_mov_b32_e32 v27, v33
	v_mov_b32_e32 v19, v30
	v_mov_b32_e32 v21, v31
	v_pk_add_f32 v[22:23], v[24:25], v[26:27]
	v_pk_add_f32 v[18:19], v[18:19], v[20:21]
	s_nop 0
	v_pk_add_f32 v[18:19], v[18:19], v[22:23]
	s_nop 0
	v_add_f32_e32 v18, v18, v19
	v_fmamk_f32 v18, v18, 0x3a800000, v156
	v_mul_f32_e32 v19, 0x4f800000, v18
	v_cmp_gt_f32_e32 vcc, s55, v18
	s_nop 1
	v_cndmask_b32_e32 v18, v18, v19, vcc
	v_sqrt_f32_e32 v19, v18
	s_nop 0
	v_add_u32_e32 v20, -1, v19
	v_add_u32_e32 v21, 1, v19
	v_fma_f32 v22, -v20, v19, v18
	v_fma_f32 v23, -v21, v19, v18
	v_cmp_ge_f32_e64 s[0:1], 0, v22
	s_nop 1
	v_cndmask_b32_e64 v19, v19, v20, s[0:1]
	v_cmp_lt_f32_e64 s[0:1], 0, v23
	s_nop 1
	v_cndmask_b32_e64 v19, v19, v21, s[0:1]
	v_mul_f32_e32 v20, 0x37800000, v19
	v_cndmask_b32_e32 v19, v19, v20, vcc
	v_cmp_class_f32_e32 vcc, v18, v157
	s_nop 1
	v_cndmask_b32_e32 v18, v19, v18, vcc
	v_div_scale_f32 v19, s[0:1], v18, v18, 1.0
	v_rcp_f32_e32 v20, v19
	v_div_scale_f32 v21, vcc, 1.0, v18, 1.0
	s_mov_b64 s[0:1], 0
	v_fma_f32 v22, -v19, v20, 1.0
	v_fmac_f32_e32 v20, v22, v20
	v_mul_f32_e32 v22, v21, v20
	v_fma_f32 v23, -v19, v22, v21
	v_fmac_f32_e32 v22, v23, v20
	v_fma_f32 v19, -v19, v22, v21
	v_div_fmas_f32 v19, v19, v20, v22
	v_div_fixup_f32 v18, v19, v18, 1.0

; __device__ __forceinline__ unsigned cvt_pk_bf16(float lo, float hi) { unsigned r; asm volatile("v_cvt_pk_bf16_f32 %0, %1, %2" : "=v"(r) : "v"(lo), "v"(hi)); return r; }
;     __device__ __forceinline__ void operator()(const f32x4 (&acc)[2][2][4][2], const Unit& u, int wr, int wc, int fr, int fq) const {
;     ...
;             for (int m = 0; m < 4; ++m) {
;                 const int row = row0 + ai * HALF + m * 16; bf16_t* rowp = O + (size_t)row * ldc + col0;
;                 const float r = (slot >= 0 ? tab[slot * 256 + (row - u.pm * BM)] : row_rstd(sspart, row, eps)) * sc;
; #pragma unroll
;                 for (int bj = 0; bj < 2; ++bj) {
;                     f32x4 v0 = acc[ai][bj][m][0] * r, v1 = acc[ai][bj][m][1] * r;
;                     if (ACT == 1) {
; #pragma unroll
;                         for (int e = 0; e < 4; ++e) { const float a = fmaxf(v0[e], 0.f), b = fmaxf(v1[e], 0.f); v0[e] = a * a; v1[e] = b * b; }
;                     }
;                     u32x4 w; w.x = cvt_pk_bf16(v0[0], v0[1]); w.y = cvt_pk_bf16(v0[2], v0[3]); w.z = cvt_pk_bf16(v1[0], v1[1]); w.w = cvt_pk_bf16(v1[2], v1[3]);
;                     *(u32x4*)(rowp + bj * HALF) = w;
;                 }
;             }
.LBB0_1384:
	s_waitcnt lgkmcnt(4)
	v_pk_mul_f32 v[8:9], v[8:9], v[18:19] op_sel_hi:[1,0]
	v_pk_mul_f32 v[12:13], v[12:13], v[18:19] op_sel_hi:[1,0]
	v_pk_mul_f32 v[10:11], v[10:11], v[18:19] op_sel_hi:[1,0]
	v_max_f32_e32 v8, 0, v8
	v_lshlrev_b64 v[16:17], 13, v[16:17]
	v_pk_mul_f32 v[14:15], v[14:15], v[18:19] op_sel_hi:[1,0]
	v_mul_f32_e32 v19, v8, v8
	v_max_f32_e32 v8, 0, v13
	v_max_f32_e32 v9, 0, v9
	v_max_f32_e32 v10, 0, v10
	v_lshl_add_u64 v[16:17], s[14:15], 0, v[16:17]
	v_max_f32_e32 v12, 0, v12
	v_mul_f32_e32 v8, v8, v8
	v_mul_f32_e32 v13, v9, v9
	v_max_f32_e32 v9, 0, v14
	v_mul_f32_e32 v14, v10, v10
	v_max_f32_e32 v10, 0, v15
	v_max_f32_e32 v11, 0, v11
	v_pk_mul_f32 v[2:3], v[2:3], v[18:19] op_sel_hi:[1,0]
	v_pk_mul_f32 v[0:1], v[0:1], v[18:19] op_sel_hi:[1,0]
	v_lshl_add_u64 v[16:17], v[146:147], 1, v[16:17]
	v_mul_f32_e32 v12, v12, v12
	v_mul_f32_e32 v9, v9, v9
	v_mul_f32_e32 v10, v10, v10
	v_mul_f32_e32 v11, v11, v11
	v_cvt_pk_bf16_f32 v8, v12, v8
	v_pk_mul_f32 v[6:7], v[6:7], v[18:19] op_sel_hi:[1,0]
	v_pk_mul_f32 v[4:5], v[4:5], v[18:19] op_sel_hi:[1,0]
	v_max_f32_e32 v0, 0, v0
	v_max_f32_e32 v1, 0, v1
	v_max_f32_e32 v2, 0, v2
	v_cvt_pk_bf16_f32 v9, v9, v10
	v_cvt_pk_bf16_f32 v10, v19, v13
	v_cvt_pk_bf16_f32 v11, v14, v11
	ds_bpermute_b32 v240, v253, v8
	ds_bpermute_b32 v241, v253, v9
	ds_bpermute_b32 v242, v253, v10
	ds_bpermute_b32 v243, v253, v11
	v_lshl_add_u64 v[236:237], v[16:17], 0, v[250:251]
	s_waitcnt lgkmcnt(4)
	global_store_dwordx4 v[238:239], v[244:247], off offset:256
	v_max_f32_e32 v3, 0, v3
	v_max_f32_e32 v4, 0, v4
	v_mul_f32_e32 v8, v0, v0
	v_max_f32_e32 v0, 0, v5
	v_mul_f32_e32 v5, v1, v1
	v_max_f32_e32 v1, 0, v6
	v_mul_f32_e32 v6, v2, v2
	v_max_f32_e32 v2, 0, v7
	v_mul_f32_e32 v0, v0, v0
	v_mul_f32_e32 v1, v1, v1
	v_mul_f32_e32 v2, v2, v2
	v_mul_f32_e32 v3, v3, v3
	s_andn2_b64 vcc, exec, s[4:5]
	s_mov_b64 s[0:1], -1
	v_mul_f32_e32 v4, v4, v4
	v_cvt_pk_bf16_f32 v0, v4, v0
	v_cvt_pk_bf16_f32 v1, v1, v2
	v_cvt_pk_bf16_f32 v2, v8, v5
	v_cvt_pk_bf16_f32 v3, v6, v3
	ds_bpermute_b32 v244, v253, v0
	ds_bpermute_b32 v245, v253, v1
	ds_bpermute_b32 v246, v253, v2
	ds_bpermute_b32 v247, v253, v3
	v_lshl_add_u64 v[238:239], v[16:17], 0, v[250:251]
	s_waitcnt lgkmcnt(4)
	global_store_dwordx4 v[236:237], v[240:243], off
	s_waitcnt lgkmcnt(0)
	global_store_dwordx4 v[238:239], v[244:247], off offset:256
	s_cbranch_vccnz .LBB0_1327
	s_andn2_b64 vcc, exec, s[12:13]
	s_cbranch_vccnz .LBB0_1326
	s_barrier
	s_branch .LBB0_1326
